# v23 + cross-lane reduction steps in GEMM epilogues (P1 norm, P4, P5, P6, P8) via v_permlane16/32_swap instead of ds_bpermute round trips
# baseline (speedup 1.0000x reference)
;     DI void operator()(Acc& acc, const Unit& u, int wr, int wc, int fr, int fq, LAS unsigned char* lds) const {
;     ...
;                     for (int bj = 0; bj < 2; ++bj) { const f32x4 v0 = acc[ai][bj][m][0], v1 = acc[ai][bj][m][1];
;                         float ss = ((v0.x * v0.x + v0.y * v0.y) + (v0.z * v0.z + v0.w * v0.w)) + ((v1.x * v1.x + v1.y * v1.y) + (v1.z * v1.z + v1.w * v1.w));
;                         ss += __shfl_xor(ss, 16); ss += __shfl_xor(ss, 32);
;                         if (fq == 0) red[(ai * 128 + wr * 64 + m * 16 + fr) * 8 + bj * 4 + wc] = ss; }
.LBB0_171:
	s_andn2_b64 vcc, exec, s[8:9]
	s_cbranch_vccnz .LBB0_205
	v_mul_f32_e32 v122, v69, v69
	v_mul_f32_e32 v123, v71, v71
	v_and_b32_e32 v121, 64, v206
	v_fmac_f32_e32 v122, v68, v68
	v_fmac_f32_e32 v123, v70, v70
	v_xor_b32_e32 v120, 16, v206
	v_add_u32_e32 v121, 64, v121
	v_add_f32_e32 v122, v122, v123
	v_mul_f32_e32 v123, v65, v65
	v_mul_f32_e32 v124, v67, v67
	v_cmp_lt_i32_e32 vcc, v120, v121
	v_fmac_f32_e32 v123, v64, v64
	v_fmac_f32_e32 v124, v66, v66
	v_cndmask_b32_e32 v120, v206, v120, vcc
	v_add_f32_e32 v123, v123, v124
	v_lshlrev_b32_e32 v120, 2, v120
	v_add_f32_e32 v122, v122, v123
	v_mov_b32_e32 v123, v122
	v_mov_b32_e32 v240, v122
	s_nop 1
	v_permlane16_swap_b32_e32 v240, v123
	v_xor_b32_e32 v124, 32, v206
	v_cmp_lt_i32_e32 vcc, v124, v121
	s_waitcnt lgkmcnt(0)
	v_add_f32_e32 v122, v240, v123
	v_cndmask_b32_e32 v121, v206, v124, vcc
	v_lshlrev_b32_e32 v121, 2, v121
	v_mov_b32_e32 v123, v122
	v_mov_b32_e32 v240, v122
	s_nop 1
	v_permlane32_swap_b32_e32 v240, v123
	s_and_saveexec_b64 s[8:9], s[4:5]
	s_cbranch_execz .LBB0_174
	s_waitcnt lgkmcnt(0)
	v_add_f32_e32 v122, v122, v123
	ds_write_b32 v184, v122
.LBB0_174:
	s_or_b64 exec, exec, s[8:9]
	v_mul_f32_e32 v122, v133, v133
	s_waitcnt lgkmcnt(0)
	v_mul_f32_e32 v123, v135, v135
	v_fmac_f32_e32 v122, v132, v132
	v_fmac_f32_e32 v123, v134, v134
	v_add_f32_e32 v122, v122, v123
	v_mul_f32_e32 v123, v129, v129
	v_mul_f32_e32 v124, v131, v131
	v_fmac_f32_e32 v123, v128, v128
	v_fmac_f32_e32 v124, v130, v130
	v_add_f32_e32 v123, v123, v124
	v_add_f32_e32 v122, v122, v123
	v_mov_b32_e32 v123, v122
	v_mov_b32_e32 v240, v122
	s_nop 1
	v_permlane16_swap_b32_e32 v240, v123
	s_waitcnt lgkmcnt(0)
	v_add_f32_e32 v122, v240, v123
	v_mov_b32_e32 v123, v122
	v_mov_b32_e32 v240, v122
	s_nop 1
	v_permlane32_swap_b32_e32 v240, v123
	s_and_saveexec_b64 s[8:9], s[4:5]
	s_cbranch_execz .LBB0_176
	s_waitcnt lgkmcnt(0)
	v_add_f32_e32 v122, v122, v123
	ds_write_b32 v184, v122 offset:16
.LBB0_176:
	s_or_b64 exec, exec, s[8:9]
	v_mul_f32_e32 v122, v61, v61
	s_waitcnt lgkmcnt(0)
	v_mul_f32_e32 v123, v63, v63
	v_fmac_f32_e32 v122, v60, v60
	v_fmac_f32_e32 v123, v62, v62
	v_add_f32_e32 v122, v122, v123
	v_mul_f32_e32 v123, v57, v57
	v_mul_f32_e32 v124, v59, v59
	v_fmac_f32_e32 v123, v56, v56
	v_fmac_f32_e32 v124, v58, v58
	v_add_f32_e32 v123, v123, v124
	v_add_f32_e32 v122, v122, v123
	v_mov_b32_e32 v123, v122
	v_mov_b32_e32 v240, v122
	s_nop 1
	v_permlane16_swap_b32_e32 v240, v123
	s_waitcnt lgkmcnt(0)
	v_add_f32_e32 v122, v240, v123
	v_mov_b32_e32 v123, v122
	v_mov_b32_e32 v240, v122
	s_nop 1
	v_permlane32_swap_b32_e32 v240, v123
	s_and_saveexec_b64 s[8:9], s[4:5]
	s_cbranch_execz .LBB0_178
	s_waitcnt lgkmcnt(0)
	v_add_f32_e32 v122, v122, v123
	ds_write_b32 v184, v122 offset:512
.LBB0_178:
	s_or_b64 exec, exec, s[8:9]
	v_mul_f32_e32 v122, v117, v117
	s_waitcnt lgkmcnt(0)
	v_mul_f32_e32 v123, v119, v119
	v_fmac_f32_e32 v122, v116, v116
	v_fmac_f32_e32 v123, v118, v118
	v_add_f32_e32 v122, v122, v123
	v_mul_f32_e32 v123, v113, v113
	v_mul_f32_e32 v124, v115, v115
	v_fmac_f32_e32 v123, v112, v112
	v_fmac_f32_e32 v124, v114, v114
	v_add_f32_e32 v123, v123, v124
	v_add_f32_e32 v122, v122, v123
	v_mov_b32_e32 v123, v122
	v_mov_b32_e32 v240, v122
	s_nop 1
	v_permlane16_swap_b32_e32 v240, v123
	s_waitcnt lgkmcnt(0)
	v_add_f32_e32 v122, v240, v123
	v_mov_b32_e32 v123, v122
	v_mov_b32_e32 v240, v122
	s_nop 1
	v_permlane32_swap_b32_e32 v240, v123
	s_and_saveexec_b64 s[8:9], s[4:5]
	s_cbranch_execz .LBB0_180
	s_waitcnt lgkmcnt(0)
	v_add_f32_e32 v122, v122, v123
	ds_write_b32 v184, v122 offset:528
.LBB0_180:
	s_or_b64 exec, exec, s[8:9]
	v_mul_f32_e32 v122, v53, v53
	s_waitcnt lgkmcnt(0)
	v_mul_f32_e32 v123, v55, v55
	v_fmac_f32_e32 v122, v52, v52
	v_fmac_f32_e32 v123, v54, v54
	v_add_f32_e32 v122, v122, v123
	v_mul_f32_e32 v123, v49, v49
	v_mul_f32_e32 v124, v51, v51
	v_fmac_f32_e32 v123, v48, v48
	v_fmac_f32_e32 v124, v50, v50
	v_add_f32_e32 v123, v123, v124
	v_add_f32_e32 v122, v122, v123
	v_mov_b32_e32 v123, v122
	v_mov_b32_e32 v240, v122
	s_nop 1
	v_permlane16_swap_b32_e32 v240, v123
	s_waitcnt lgkmcnt(0)
	v_add_f32_e32 v122, v240, v123
	v_mov_b32_e32 v123, v122
	v_mov_b32_e32 v240, v122
	s_nop 1
	v_permlane32_swap_b32_e32 v240, v123
	s_and_saveexec_b64 s[8:9], s[4:5]
	s_cbranch_execz .LBB0_182
	s_waitcnt lgkmcnt(0)
	v_add_f32_e32 v122, v122, v123
	ds_write_b32 v184, v122 offset:1024
.LBB0_182:
	s_or_b64 exec, exec, s[8:9]
	v_mul_f32_e32 v122, v109, v109
	s_waitcnt lgkmcnt(0)
	v_mul_f32_e32 v123, v111, v111
	v_fmac_f32_e32 v122, v108, v108
	v_fmac_f32_e32 v123, v110, v110
	v_add_f32_e32 v122, v122, v123
	v_mul_f32_e32 v123, v105, v105
	v_mul_f32_e32 v124, v107, v107
	v_fmac_f32_e32 v123, v104, v104
	v_fmac_f32_e32 v124, v106, v106
	v_add_f32_e32 v123, v123, v124
	v_add_f32_e32 v122, v122, v123
	v_mov_b32_e32 v123, v122
	v_mov_b32_e32 v240, v122
	s_nop 1
	v_permlane16_swap_b32_e32 v240, v123
	s_waitcnt lgkmcnt(0)
	v_add_f32_e32 v122, v240, v123
	v_mov_b32_e32 v123, v122
	v_mov_b32_e32 v240, v122
	s_nop 1
	v_permlane32_swap_b32_e32 v240, v123
	s_and_saveexec_b64 s[8:9], s[4:5]
	s_cbranch_execz .LBB0_184
	s_waitcnt lgkmcnt(0)
	v_add_f32_e32 v122, v122, v123
	ds_write_b32 v184, v122 offset:1040
.LBB0_184:
	s_or_b64 exec, exec, s[8:9]
	v_mul_f32_e32 v122, v45, v45
	s_waitcnt lgkmcnt(0)
	v_mul_f32_e32 v123, v47, v47
	v_fmac_f32_e32 v122, v44, v44
	v_fmac_f32_e32 v123, v46, v46
	v_add_f32_e32 v122, v122, v123
	v_mul_f32_e32 v123, v41, v41
	v_mul_f32_e32 v124, v43, v43
	v_fmac_f32_e32 v123, v40, v40
	v_fmac_f32_e32 v124, v42, v42
	v_add_f32_e32 v123, v123, v124
	v_add_f32_e32 v122, v122, v123
	v_mov_b32_e32 v123, v122
	v_mov_b32_e32 v240, v122
	s_nop 1
	v_permlane16_swap_b32_e32 v240, v123
	s_waitcnt lgkmcnt(0)
	v_add_f32_e32 v122, v240, v123
	v_mov_b32_e32 v123, v122
	v_mov_b32_e32 v240, v122
	s_nop 1
	v_permlane32_swap_b32_e32 v240, v123
	s_and_saveexec_b64 s[8:9], s[4:5]
	s_cbranch_execz .LBB0_186
	s_waitcnt lgkmcnt(0)
	v_add_f32_e32 v122, v122, v123
	ds_write_b32 v184, v122 offset:1536
;     DI void operator()(Acc& acc, const Unit& u, int wr, int wc, int fr, int fq, LAS unsigned char* lds) const {
;     ...
;                     for (int bj = 0; bj < 2; ++bj) { const f32x4 v0 = acc[ai][bj][m][0], v1 = acc[ai][bj][m][1];
;                         float ss = ((v0.x * v0.x + v0.y * v0.y) + (v0.z * v0.z + v0.w * v0.w)) + ((v1.x * v1.x + v1.y * v1.y) + (v1.z * v1.z + v1.w * v1.w));
;                         ss += __shfl_xor(ss, 16); ss += __shfl_xor(ss, 32);
;                         if (fq == 0) red[(ai * 128 + wr * 64 + m * 16 + fr) * 8 + bj * 4 + wc] = ss; }
.LBB0_186:
	s_or_b64 exec, exec, s[8:9]
	v_mul_f32_e32 v122, v101, v101
	s_waitcnt lgkmcnt(0)
	v_mul_f32_e32 v123, v103, v103
	v_fmac_f32_e32 v122, v100, v100
	v_fmac_f32_e32 v123, v102, v102
	v_add_f32_e32 v122, v122, v123
	v_mul_f32_e32 v123, v97, v97
	v_mul_f32_e32 v124, v99, v99
	v_fmac_f32_e32 v123, v96, v96
	v_fmac_f32_e32 v124, v98, v98
	v_add_f32_e32 v123, v123, v124
	v_add_f32_e32 v122, v122, v123
	v_mov_b32_e32 v123, v122
	v_mov_b32_e32 v240, v122
	s_nop 1
	v_permlane16_swap_b32_e32 v240, v123
	s_waitcnt lgkmcnt(0)
	v_add_f32_e32 v122, v240, v123
	v_mov_b32_e32 v123, v122
	v_mov_b32_e32 v240, v122
	s_nop 1
	v_permlane32_swap_b32_e32 v240, v123
	s_and_saveexec_b64 s[8:9], s[4:5]
	s_cbranch_execz .LBB0_188
	s_waitcnt lgkmcnt(0)
	v_add_f32_e32 v122, v122, v123
	ds_write_b32 v184, v122 offset:1552
.LBB0_188:
	s_or_b64 exec, exec, s[8:9]
	v_mul_f32_e32 v122, v29, v29
	s_waitcnt lgkmcnt(0)
	v_mul_f32_e32 v123, v31, v31
	v_fmac_f32_e32 v122, v28, v28
	v_fmac_f32_e32 v123, v30, v30
	v_add_f32_e32 v122, v122, v123
	v_mul_f32_e32 v123, v25, v25
	v_mul_f32_e32 v124, v27, v27
	v_fmac_f32_e32 v123, v24, v24
	v_fmac_f32_e32 v124, v26, v26
	v_add_f32_e32 v123, v123, v124
	v_add_f32_e32 v122, v122, v123
	v_mov_b32_e32 v123, v122
	v_mov_b32_e32 v240, v122
	s_nop 1
	v_permlane16_swap_b32_e32 v240, v123
	s_waitcnt lgkmcnt(0)
	v_add_f32_e32 v122, v240, v123
	v_mov_b32_e32 v123, v122
	v_mov_b32_e32 v240, v122
	s_nop 1
	v_permlane32_swap_b32_e32 v240, v123
	s_and_saveexec_b64 s[8:9], s[4:5]
	s_cbranch_execz .LBB0_190
	s_waitcnt lgkmcnt(0)
	v_add_f32_e32 v122, v122, v123
	ds_write_b32 v184, v122 offset:4096
.LBB0_190:
	s_or_b64 exec, exec, s[8:9]
	v_mul_f32_e32 v122, v93, v93
	s_waitcnt lgkmcnt(0)
	v_mul_f32_e32 v123, v95, v95
	v_fmac_f32_e32 v122, v92, v92
	v_fmac_f32_e32 v123, v94, v94
	v_add_f32_e32 v122, v122, v123
	v_mul_f32_e32 v123, v89, v89
	v_mul_f32_e32 v124, v91, v91
	v_fmac_f32_e32 v123, v88, v88
	v_fmac_f32_e32 v124, v90, v90
	v_add_f32_e32 v123, v123, v124
	v_add_f32_e32 v122, v122, v123
	v_mov_b32_e32 v123, v122
	v_mov_b32_e32 v240, v122
	s_nop 1
	v_permlane16_swap_b32_e32 v240, v123
	s_waitcnt lgkmcnt(0)
	v_add_f32_e32 v122, v240, v123
	v_mov_b32_e32 v123, v122
	v_mov_b32_e32 v240, v122
	s_nop 1
	v_permlane32_swap_b32_e32 v240, v123
	s_and_saveexec_b64 s[8:9], s[4:5]
	s_cbranch_execz .LBB0_192
	s_waitcnt lgkmcnt(0)
	v_add_f32_e32 v122, v122, v123
	ds_write_b32 v184, v122 offset:4112
.LBB0_192:
	s_or_b64 exec, exec, s[8:9]
	v_mul_f32_e32 v122, v21, v21
	s_waitcnt lgkmcnt(0)
	v_mul_f32_e32 v123, v23, v23
	v_fmac_f32_e32 v122, v20, v20
	v_fmac_f32_e32 v123, v22, v22
	v_add_f32_e32 v122, v122, v123
	v_mul_f32_e32 v123, v17, v17
	v_mul_f32_e32 v124, v19, v19
	v_fmac_f32_e32 v123, v16, v16
	v_fmac_f32_e32 v124, v18, v18
	v_add_f32_e32 v123, v123, v124
	v_add_f32_e32 v122, v122, v123
	v_mov_b32_e32 v123, v122
	v_mov_b32_e32 v240, v122
	s_nop 1
	v_permlane16_swap_b32_e32 v240, v123
	s_waitcnt lgkmcnt(0)
	v_add_f32_e32 v122, v240, v123
	v_mov_b32_e32 v123, v122
	v_mov_b32_e32 v240, v122
	s_nop 1
	v_permlane32_swap_b32_e32 v240, v123
	s_and_saveexec_b64 s[8:9], s[4:5]
	s_cbranch_execz .LBB0_194
	s_waitcnt lgkmcnt(0)
	v_add_f32_e32 v122, v122, v123
	ds_write_b32 v184, v122 offset:4608
;     DI void operator()(Acc& acc, const Unit& u, int wr, int wc, int fr, int fq, LAS unsigned char* lds) const {
;     ...
;                     for (int bj = 0; bj < 2; ++bj) { const f32x4 v0 = acc[ai][bj][m][0], v1 = acc[ai][bj][m][1];
;                         float ss = ((v0.x * v0.x + v0.y * v0.y) + (v0.z * v0.z + v0.w * v0.w)) + ((v1.x * v1.x + v1.y * v1.y) + (v1.z * v1.z + v1.w * v1.w));
;                         ss += __shfl_xor(ss, 16); ss += __shfl_xor(ss, 32);
;                         if (fq == 0) red[(ai * 128 + wr * 64 + m * 16 + fr) * 8 + bj * 4 + wc] = ss; }
.LBB0_194:
	s_or_b64 exec, exec, s[8:9]
	v_mul_f32_e32 v122, v85, v85
	s_waitcnt lgkmcnt(0)
	v_mul_f32_e32 v123, v87, v87
	v_fmac_f32_e32 v122, v84, v84
	v_fmac_f32_e32 v123, v86, v86
	v_add_f32_e32 v122, v122, v123
	v_mul_f32_e32 v123, v81, v81
	v_mul_f32_e32 v124, v83, v83
	v_fmac_f32_e32 v123, v80, v80
	v_fmac_f32_e32 v124, v82, v82
	v_add_f32_e32 v123, v123, v124
	v_add_f32_e32 v122, v122, v123
	v_mov_b32_e32 v123, v122
	v_mov_b32_e32 v240, v122
	s_nop 1
	v_permlane16_swap_b32_e32 v240, v123
	s_waitcnt lgkmcnt(0)
	v_add_f32_e32 v122, v240, v123
	v_mov_b32_e32 v123, v122
	v_mov_b32_e32 v240, v122
	s_nop 1
	v_permlane32_swap_b32_e32 v240, v123
	s_and_saveexec_b64 s[8:9], s[4:5]
	s_cbranch_execz .LBB0_196
	s_waitcnt lgkmcnt(0)
	v_add_f32_e32 v122, v122, v123
	ds_write_b32 v184, v122 offset:4624
.LBB0_196:
	s_or_b64 exec, exec, s[8:9]
	v_mul_f32_e32 v122, v13, v13
	s_waitcnt lgkmcnt(0)
	v_mul_f32_e32 v123, v15, v15
	v_fmac_f32_e32 v122, v12, v12
	v_fmac_f32_e32 v123, v14, v14
	v_add_f32_e32 v122, v122, v123
	v_mul_f32_e32 v123, v9, v9
	v_mul_f32_e32 v124, v11, v11
	v_fmac_f32_e32 v123, v8, v8
	v_fmac_f32_e32 v124, v10, v10
	v_add_f32_e32 v123, v123, v124
	v_add_f32_e32 v122, v122, v123
	v_mov_b32_e32 v123, v122
	v_mov_b32_e32 v240, v122
	s_nop 1
	v_permlane16_swap_b32_e32 v240, v123
	s_waitcnt lgkmcnt(0)
	v_add_f32_e32 v122, v240, v123
	v_mov_b32_e32 v123, v122
	v_mov_b32_e32 v240, v122
	s_nop 1
	v_permlane32_swap_b32_e32 v240, v123
	s_and_saveexec_b64 s[8:9], s[4:5]
	s_cbranch_execz .LBB0_198
	s_waitcnt lgkmcnt(0)
	v_add_f32_e32 v122, v122, v123
	ds_write_b32 v184, v122 offset:5120
.LBB0_198:
	s_or_b64 exec, exec, s[8:9]
	v_mul_f32_e32 v122, v77, v77
	s_waitcnt lgkmcnt(0)
	v_mul_f32_e32 v123, v79, v79
	v_fmac_f32_e32 v122, v76, v76
	v_fmac_f32_e32 v123, v78, v78
	v_add_f32_e32 v122, v122, v123
	v_mul_f32_e32 v123, v73, v73
	v_mul_f32_e32 v124, v75, v75
	v_fmac_f32_e32 v123, v72, v72
	v_fmac_f32_e32 v124, v74, v74
	v_add_f32_e32 v123, v123, v124
	v_add_f32_e32 v122, v122, v123
	v_mov_b32_e32 v123, v122
	v_mov_b32_e32 v240, v122
	s_nop 1
	v_permlane16_swap_b32_e32 v240, v123
	s_waitcnt lgkmcnt(0)
	v_add_f32_e32 v122, v240, v123
	v_mov_b32_e32 v123, v122
	v_mov_b32_e32 v240, v122
	s_nop 1
	v_permlane32_swap_b32_e32 v240, v123
	s_and_saveexec_b64 s[8:9], s[4:5]
	s_cbranch_execz .LBB0_200
	s_waitcnt lgkmcnt(0)
	v_add_f32_e32 v122, v122, v123
	ds_write_b32 v184, v122 offset:5136
.LBB0_200:
	s_or_b64 exec, exec, s[8:9]
	v_mul_f32_e32 v122, v5, v5
	s_waitcnt lgkmcnt(0)
	v_mul_f32_e32 v123, v7, v7
	v_fmac_f32_e32 v122, v4, v4
	v_fmac_f32_e32 v123, v6, v6
	v_add_f32_e32 v122, v122, v123
	v_mul_f32_e32 v123, v1, v1
	v_mul_f32_e32 v124, v3, v3
	v_fmac_f32_e32 v123, v0, v0
	v_fmac_f32_e32 v124, v2, v2
	v_add_f32_e32 v123, v123, v124
	v_add_f32_e32 v122, v122, v123
	v_mov_b32_e32 v123, v122
	v_mov_b32_e32 v240, v122
	s_nop 1
	v_permlane16_swap_b32_e32 v240, v123
	s_waitcnt lgkmcnt(0)
	v_add_f32_e32 v122, v240, v123
	v_mov_b32_e32 v123, v122
	v_mov_b32_e32 v240, v122
	s_nop 1
	v_permlane32_swap_b32_e32 v240, v123
	s_and_saveexec_b64 s[8:9], s[4:5]
	s_cbranch_execz .LBB0_202
	s_waitcnt lgkmcnt(0)
	v_add_f32_e32 v122, v122, v123
	ds_write_b32 v184, v122 offset:5632
.LBB0_202:
	s_or_b64 exec, exec, s[8:9]
	v_mul_f32_e32 v122, v37, v37
	s_waitcnt lgkmcnt(0)
	v_mul_f32_e32 v123, v39, v39
	v_fmac_f32_e32 v122, v36, v36
	v_fmac_f32_e32 v123, v38, v38
	v_add_f32_e32 v122, v122, v123
	v_mul_f32_e32 v123, v33, v33
	v_mul_f32_e32 v124, v35, v35
	v_fmac_f32_e32 v123, v32, v32
	v_fmac_f32_e32 v124, v34, v34
	v_add_f32_e32 v123, v123, v124
	v_add_f32_e32 v122, v122, v123
	v_mov_b32_e32 v120, v122
	v_mov_b32_e32 v240, v122
	s_nop 1
	v_permlane16_swap_b32_e32 v240, v120
	s_waitcnt lgkmcnt(0)
	v_add_f32_e32 v120, v240, v120
	v_mov_b32_e32 v121, v120
	v_mov_b32_e32 v240, v120
	s_nop 1
	v_permlane32_swap_b32_e32 v240, v121
	s_and_saveexec_b64 s[8:9], s[4:5]
	s_cbranch_execz .LBB0_204
	s_waitcnt lgkmcnt(0)
	v_add_f32_e32 v120, v120, v121
	ds_write_b32 v184, v120 offset:5648

; DI unsigned pk2(float lo, float hi) { f32x2 v = {lo, hi}; bf16x2_t b = __builtin_convertvector(v, bf16x2_t); return __builtin_bit_cast(unsigned, b); }
; DI float bflo(unsigned w) { return __uint_as_float(w << 16); }
; DI float bfhi(unsigned w) { return __uint_as_float(w & 0xffff0000u); }
; template <bool ISMAX> DI void tile_row_reduce(float (&p)[2][4], LAS float* red, int wr, int wc, int fr, int fq) {
;     ...
;         for (int m = 0; m < 4; ++m) { float v = p[ai][m]; const float a = __shfl_xor(v, 16); v = ISMAX ? fmaxf(v, a) : v + a; const float b = __shfl_xor(v, 32); v = ISMAX ? fmaxf(v, b) : v + b;
;             if (fq == 0) red[(ai * 128 + wr * 64 + m * 16 + fr) * 4 + wc] = v; }
;     DI void operator()(Acc& acc, const Unit& u, int wr, int wc, int fr, int fq, LAS unsigned char* lds) const {
;     ...
;             for (int m = 0; m < 4; ++m) { const int row = u.pm * BM + ai * HALF + wr * 64 + m * 16 + fr; const size_t off = (size_t)row * DM + col0; float ss = 0.f;
; #pragma unroll
;                 for (int bj = 0; bj < 2; ++bj) { const size_t o = off + bj * HALF;
;                     f32x4 b0, b1;
;                     if (BASE_BF16) { const u32x4 w = *(const u32x4*)((const bf16_t*)base + o); b0 = (f32x4){bflo(w.x), bfhi(w.x), bflo(w.y), bfhi(w.y)}; b1 = (f32x4){bflo(w.z), bfhi(w.z), bflo(w.w), bfhi(w.w)}; }
;                     else { b0 = *(const f32x4*)((const float*)base + o); b1 = *(const f32x4*)((const float*)base + o + 4); }
;                     const f32x4 v0 = b0 + acc[ai][bj][m][0], v1 = b1 + acc[ai][bj][m][1];
;                     if (OUT_F32) { __builtin_nontemporal_store(v0, (f32x4*)(out + o)); __builtin_nontemporal_store(v1, (f32x4*)(out + o + 4)); }
;                     if (OUT_BF16) { u32x4 w; w.x = pk2(v0.x, v0.y); w.y = pk2(v0.z, v0.w); w.z = pk2(v1.x, v1.y); w.w = pk2(v1.z, v1.w); *(u32x4*)(hb + o) = w;
;                         ss += ((v0.x * v0.x + v0.y * v0.y) + (v0.z * v0.z + v0.w * v0.w)) + ((v1.x * v1.x + v1.y * v1.y) + (v1.z * v1.z + v1.w * v1.w)); } }
;                 part[ai][m] = ss; }
.LBB0_694:
	v_lshl_add_u32 v144, s52, 8, v148
	v_lshl_or_b32 v146, s20, 8, v150
	v_ashrrev_i32_e32 v145, 31, v144
	v_ashrrev_i32_e32 v147, 31, v146
	v_lshlrev_b64 v[156:157], 10, v[144:145]
	v_lshl_add_u64 v[160:161], v[156:157], 0, v[146:147]
	v_lshl_add_u64 v[170:171], v[160:161], 2, s[16:17]
	global_load_dwordx4 v[156:159], v[170:171], off offset:16
	global_load_dwordx4 v[166:169], v[170:171], off
	v_lshlrev_b64 v[160:161], 1, v[160:161]
	s_waitcnt vmcnt(0)
	v_pk_add_f32 v[158:159], v[122:123], v[158:159]
	v_pk_add_f32 v[126:127], v[126:127], v[168:169]
	v_pk_add_f32 v[124:125], v[124:125], v[166:167]
	v_pk_add_f32 v[156:157], v[120:121], v[156:157]
	v_cvt_pk_bf16_f32 v120, v124, v125
	v_cvt_pk_bf16_f32 v121, v126, v127
	v_cvt_pk_bf16_f32 v122, v156, v157
	v_cvt_pk_bf16_f32 v123, v158, v159
	v_lshl_add_u64 v[166:167], s[26:27], 0, v[160:161]
	global_store_dwordx4 v[166:167], v[120:123], off
	v_or_b32_e32 v160, 0x100, v160
	s_nop 0
	v_mul_f32_e32 v120, v125, v125
	v_mul_f32_e32 v121, v127, v127
	v_fmac_f32_e32 v120, v124, v124
	v_fmac_f32_e32 v121, v126, v126
	v_add_f32_e32 v120, v120, v121
	v_mul_f32_e32 v121, v157, v157
	v_mul_f32_e32 v122, v159, v159
	v_fmac_f32_e32 v121, v156, v156
	v_fmac_f32_e32 v122, v158, v158
	v_add_f32_e32 v121, v121, v122
	v_add_f32_e32 v155, v120, v121
	global_load_dwordx4 v[120:123], v[170:171], off offset:528
	global_load_dwordx4 v[124:127], v[170:171], off offset:512
	s_waitcnt vmcnt(1)
	v_pk_add_f32 v[122:123], v[114:115], v[122:123]
	s_waitcnt vmcnt(0)
	v_pk_add_f32 v[118:119], v[118:119], v[126:127]
	v_pk_add_f32 v[116:117], v[116:117], v[124:125]
	v_pk_add_f32 v[120:121], v[112:113], v[120:121]
	v_cvt_pk_bf16_f32 v112, v116, v117
	v_cvt_pk_bf16_f32 v113, v118, v119
	v_cvt_pk_bf16_f32 v114, v120, v121
	v_cvt_pk_bf16_f32 v115, v122, v123
	v_lshl_add_u64 v[124:125], s[26:27], 0, v[160:161]
	global_store_dwordx4 v[124:125], v[112:115], off
	s_nop 1
	v_mul_f32_e32 v112, v117, v117
	v_mul_f32_e32 v113, v119, v119
	v_fmac_f32_e32 v112, v116, v116
	v_fmac_f32_e32 v113, v118, v118
	v_add_f32_e32 v112, v112, v113
	v_mul_f32_e32 v113, v121, v121
	v_mul_f32_e32 v114, v123, v123
	v_fmac_f32_e32 v113, v120, v120
	v_fmac_f32_e32 v114, v122, v122
	v_add_f32_e32 v113, v113, v114
	v_add_f32_e32 v112, v112, v113
	v_add_f32_e32 v126, v155, v112
	v_or_b32_e32 v112, 16, v144
	v_ashrrev_i32_e32 v113, 31, v112
	v_lshlrev_b64 v[114:115], 10, v[112:113]
	v_lshl_add_u64 v[122:123], v[114:115], 0, v[146:147]
	v_lshl_add_u64 v[124:125], v[122:123], 2, s[16:17]
	global_load_dwordx4 v[114:117], v[124:125], off offset:16
	global_load_dwordx4 v[118:121], v[124:125], off
	v_lshlrev_b64 v[156:157], 1, v[122:123]
	v_mov_b32_e32 v127, v126
	v_mov_b32_e32 v250, v126
	s_nop 1
	v_permlane16_swap_b32_e32 v250, v127
	s_waitcnt lgkmcnt(0)
	v_add_f32_e32 v127, v250, v127
	v_add_u32_e32 v126, s18, v151
	s_waitcnt vmcnt(1)
	v_pk_add_f32 v[106:107], v[106:107], v[116:117]
	s_waitcnt vmcnt(0)
	v_pk_add_f32 v[110:111], v[110:111], v[120:121]
	v_pk_add_f32 v[108:109], v[108:109], v[118:119]
	v_pk_add_f32 v[104:105], v[104:105], v[114:115]
	v_cvt_pk_bf16_f32 v114, v108, v109
	v_cvt_pk_bf16_f32 v115, v110, v111
	v_cvt_pk_bf16_f32 v116, v104, v105
	v_cvt_pk_bf16_f32 v117, v106, v107
	v_lshl_add_u64 v[118:119], s[26:27], 0, v[156:157]
	global_store_dwordx4 v[118:119], v[114:117], off
	global_load_dwordx4 v[116:119], v[124:125], off offset:528
	s_nop 0
	global_load_dwordx4 v[120:123], v[124:125], off offset:512
	v_or_b32_e32 v156, 0x100, v156
	s_waitcnt vmcnt(1)
	v_pk_add_f32 v[98:99], v[98:99], v[118:119]
	s_waitcnt vmcnt(0)
	v_pk_add_f32 v[102:103], v[102:103], v[122:123]
	v_pk_add_f32 v[114:115], v[100:101], v[120:121]
	v_pk_add_f32 v[100:101], v[96:97], v[116:117]
	v_cvt_pk_bf16_f32 v116, v114, v115
	v_cvt_pk_bf16_f32 v117, v102, v103
	v_cvt_pk_bf16_f32 v118, v100, v101
	v_cvt_pk_bf16_f32 v119, v98, v99
	v_lshl_add_u64 v[96:97], s[26:27], 0, v[156:157]
	global_store_dwordx4 v[96:97], v[116:119], off
	v_or_b32_e32 v96, 32, v144
	v_ashrrev_i32_e32 v97, 31, v96
	v_lshlrev_b64 v[116:117], 10, v[96:97]
	v_lshl_add_u64 v[124:125], v[116:117], 0, v[146:147]
	v_lshl_add_u64 v[156:157], v[124:125], 2, s[16:17]
	global_load_dwordx4 v[116:119], v[156:157], off offset:16
	global_load_dwordx4 v[120:123], v[156:157], off
	v_lshlrev_b64 v[158:159], 1, v[124:125]
	s_waitcnt vmcnt(1)
	v_pk_add_f32 v[90:91], v[90:91], v[118:119]
	s_waitcnt vmcnt(0)
	v_pk_add_f32 v[94:95], v[94:95], v[122:123]
	v_pk_add_f32 v[92:93], v[92:93], v[120:121]
	v_pk_add_f32 v[88:89], v[88:89], v[116:117]
	v_cvt_pk_bf16_f32 v116, v92, v93
	v_cvt_pk_bf16_f32 v117, v94, v95
	v_cvt_pk_bf16_f32 v118, v88, v89
	v_cvt_pk_bf16_f32 v119, v90, v91
	v_lshl_add_u64 v[120:121], s[26:27], 0, v[158:159]
	global_store_dwordx4 v[120:121], v[116:119], off
	global_load_dwordx4 v[118:121], v[156:157], off offset:528
	s_nop 0
	global_load_dwordx4 v[122:125], v[156:157], off offset:512
	v_or_b32_e32 v158, 0x100, v158
	s_waitcnt vmcnt(1)
	v_pk_add_f32 v[82:83], v[82:83], v[120:121]
	s_waitcnt vmcnt(0)
	v_pk_add_f32 v[86:87], v[86:87], v[124:125]
	v_pk_add_f32 v[116:117], v[84:85], v[122:123]
	v_pk_add_f32 v[84:85], v[80:81], v[118:119]
	v_cvt_pk_bf16_f32 v118, v116, v117
	v_cvt_pk_bf16_f32 v119, v86, v87
	v_cvt_pk_bf16_f32 v120, v84, v85
	v_cvt_pk_bf16_f32 v121, v82, v83
	v_lshl_add_u64 v[80:81], s[26:27], 0, v[158:159]
	global_store_dwordx4 v[80:81], v[118:121], off
	v_or_b32_e32 v80, 48, v144
	v_ashrrev_i32_e32 v81, 31, v80
	v_lshlrev_b64 v[118:119], 10, v[80:81]
	v_lshl_add_u64 v[156:157], v[118:119], 0, v[146:147]
	v_lshl_add_u64 v[158:159], v[156:157], 2, s[16:17]
	global_load_dwordx4 v[118:121], v[158:159], off offset:16
	global_load_dwordx4 v[122:125], v[158:159], off
	s_waitcnt vmcnt(1)
; DI unsigned pk2(float lo, float hi) { f32x2 v = {lo, hi}; bf16x2_t b = __builtin_convertvector(v, bf16x2_t); return __builtin_bit_cast(unsigned, b); }
; DI float bflo(unsigned w) { return __uint_as_float(w << 16); }
; DI float bfhi(unsigned w) { return __uint_as_float(w & 0xffff0000u); }
; template <bool ISMAX> DI void tile_row_reduce(float (&p)[2][4], LAS float* red, int wr, int wc, int fr, int fq) {
;     ...
;         for (int m = 0; m < 4; ++m) { float v = p[ai][m]; const float a = __shfl_xor(v, 16); v = ISMAX ? fmaxf(v, a) : v + a; const float b = __shfl_xor(v, 32); v = ISMAX ? fmaxf(v, b) : v + b;
;     DI void operator()(Acc& acc, const Unit& u, int wr, int wc, int fr, int fq, LAS unsigned char* lds) const {
;     ...
;             for (int m = 0; m < 4; ++m) { const int row = u.pm * BM + ai * HALF + wr * 64 + m * 16 + fr; const size_t off = (size_t)row * DM + col0; float ss = 0.f;
; #pragma unroll
;                 for (int bj = 0; bj < 2; ++bj) { const size_t o = off + bj * HALF;
;                     f32x4 b0, b1;
;                     if (BASE_BF16) { const u32x4 w = *(const u32x4*)((const bf16_t*)base + o); b0 = (f32x4){bflo(w.x), bfhi(w.x), bflo(w.y), bfhi(w.y)}; b1 = (f32x4){bflo(w.z), bfhi(w.z), bflo(w.w), bfhi(w.w)}; }
;                     else { b0 = *(const f32x4*)((const float*)base + o); b1 = *(const f32x4*)((const float*)base + o + 4); }
;                     const f32x4 v0 = b0 + acc[ai][bj][m][0], v1 = b1 + acc[ai][bj][m][1];
;                     if (OUT_F32) { __builtin_nontemporal_store(v0, (f32x4*)(out + o)); __builtin_nontemporal_store(v1, (f32x4*)(out + o + 4)); }
;                     if (OUT_BF16) { u32x4 w; w.x = pk2(v0.x, v0.y); w.y = pk2(v0.z, v0.w); w.z = pk2(v1.x, v1.y); w.w = pk2(v1.z, v1.w); *(u32x4*)(hb + o) = w;
;                         ss += ((v0.x * v0.x + v0.y * v0.y) + (v0.z * v0.z + v0.w * v0.w)) + ((v1.x * v1.x + v1.y * v1.y) + (v1.z * v1.z + v1.w * v1.w)); } }
;                 part[ai][m] = ss; }
	v_pk_add_f32 v[74:75], v[74:75], v[120:121]
	s_waitcnt vmcnt(0)
	v_pk_add_f32 v[78:79], v[78:79], v[124:125]
	v_pk_add_f32 v[76:77], v[76:77], v[122:123]
	v_pk_add_f32 v[72:73], v[72:73], v[118:119]
	v_lshlrev_b64 v[124:125], 1, v[156:157]
	v_cvt_pk_bf16_f32 v118, v76, v77
	v_cvt_pk_bf16_f32 v119, v78, v79
	v_cvt_pk_bf16_f32 v120, v72, v73
	v_cvt_pk_bf16_f32 v121, v74, v75
	v_lshl_add_u64 v[122:123], s[26:27], 0, v[124:125]
	global_store_dwordx4 v[122:123], v[118:121], off
	global_load_dwordx4 v[120:123], v[158:159], off offset:528
	s_nop 0
	global_load_dwordx4 v[156:159], v[158:159], off offset:512
	v_or_b32_e32 v124, 0x100, v124
	s_waitcnt vmcnt(1)
	v_pk_add_f32 v[66:67], v[66:67], v[122:123]
	s_waitcnt vmcnt(0)
	v_pk_add_f32 v[70:71], v[70:71], v[158:159]
	v_pk_add_f32 v[118:119], v[68:69], v[156:157]
	v_pk_add_f32 v[68:69], v[64:65], v[120:121]
	v_cvt_pk_bf16_f32 v120, v118, v119
	v_cvt_pk_bf16_f32 v121, v70, v71
	v_cvt_pk_bf16_f32 v122, v68, v69
	v_cvt_pk_bf16_f32 v123, v66, v67
	v_lshl_add_u64 v[64:65], s[26:27], 0, v[124:125]
	global_store_dwordx4 v[64:65], v[120:123], off
	v_add_u32_e32 v64, 0x80, v144
	v_ashrrev_i32_e32 v65, 31, v64
	v_lshlrev_b64 v[120:121], 10, v[64:65]
	v_lshl_add_u64 v[124:125], v[120:121], 0, v[146:147]
	v_lshl_add_u64 v[160:161], v[124:125], 2, s[16:17]
	global_load_dwordx4 v[120:123], v[160:161], off offset:16
	global_load_dwordx4 v[156:159], v[160:161], off
	v_lshlrev_b64 v[166:167], 1, v[124:125]
	v_lshl_add_u64 v[124:125], s[26:27], 0, v[166:167]
	v_or_b32_e32 v166, 0x100, v166
	s_waitcnt vmcnt(1)
	v_pk_add_f32 v[58:59], v[58:59], v[122:123]
	s_waitcnt vmcnt(0)
	v_pk_add_f32 v[62:63], v[62:63], v[158:159]
	v_pk_add_f32 v[60:61], v[60:61], v[156:157]
	v_pk_add_f32 v[56:57], v[56:57], v[120:121]
	v_cvt_pk_bf16_f32 v120, v60, v61
	v_cvt_pk_bf16_f32 v121, v62, v63
	v_cvt_pk_bf16_f32 v122, v56, v57
	v_cvt_pk_bf16_f32 v123, v58, v59
	global_store_dwordx4 v[124:125], v[120:123], off
	global_load_dwordx4 v[122:125], v[160:161], off offset:528
	s_nop 0
	global_load_dwordx4 v[156:159], v[160:161], off offset:512
	s_waitcnt vmcnt(1)
	v_pk_add_f32 v[50:51], v[50:51], v[124:125]
	s_waitcnt vmcnt(0)
	v_pk_add_f32 v[54:55], v[54:55], v[158:159]
	v_pk_add_f32 v[120:121], v[52:53], v[156:157]
	v_pk_add_f32 v[52:53], v[48:49], v[122:123]
	v_cvt_pk_bf16_f32 v122, v120, v121
	v_cvt_pk_bf16_f32 v123, v54, v55
	v_cvt_pk_bf16_f32 v124, v52, v53
	v_cvt_pk_bf16_f32 v125, v50, v51
	v_lshl_add_u64 v[48:49], s[26:27], 0, v[166:167]
	global_store_dwordx4 v[48:49], v[122:125], off
	v_add_u32_e32 v48, 0x90, v144
	v_ashrrev_i32_e32 v49, 31, v48
	v_lshlrev_b64 v[122:123], 10, v[48:49]
	v_lshl_add_u64 v[160:161], v[122:123], 0, v[146:147]
	v_lshl_add_u64 v[166:167], v[160:161], 2, s[16:17]
	global_load_dwordx4 v[122:125], v[166:167], off offset:16
	global_load_dwordx4 v[156:159], v[166:167], off
	v_lshlrev_b64 v[160:161], 1, v[160:161]
	s_waitcnt vmcnt(1)
	v_pk_add_f32 v[42:43], v[42:43], v[124:125]
	s_waitcnt vmcnt(0)
	v_pk_add_f32 v[46:47], v[46:47], v[158:159]
	v_pk_add_f32 v[44:45], v[44:45], v[156:157]
	v_pk_add_f32 v[40:41], v[40:41], v[122:123]
	v_cvt_pk_bf16_f32 v122, v44, v45
	v_cvt_pk_bf16_f32 v123, v46, v47
	v_cvt_pk_bf16_f32 v124, v40, v41
	v_cvt_pk_bf16_f32 v125, v42, v43
	v_lshl_add_u64 v[156:157], s[26:27], 0, v[160:161]
	global_store_dwordx4 v[156:157], v[122:125], off
	global_load_dwordx4 v[156:159], v[166:167], off offset:528
	s_nop 0
	global_load_dwordx4 v[122:125], v[166:167], off offset:512
	v_or_b32_e32 v160, 0x100, v160
	s_waitcnt vmcnt(1)
	v_pk_add_f32 v[34:35], v[34:35], v[158:159]
	s_waitcnt vmcnt(0)
	v_pk_add_f32 v[38:39], v[38:39], v[124:125]
	v_pk_add_f32 v[122:123], v[36:37], v[122:123]
	v_pk_add_f32 v[36:37], v[32:33], v[156:157]
	v_cvt_pk_bf16_f32 v156, v122, v123
	v_cvt_pk_bf16_f32 v157, v38, v39
	v_cvt_pk_bf16_f32 v158, v36, v37
	v_cvt_pk_bf16_f32 v159, v34, v35
	v_lshl_add_u64 v[32:33], s[26:27], 0, v[160:161]
	global_store_dwordx4 v[32:33], v[156:159], off
	v_add_u32_e32 v32, 0xa0, v144
	v_ashrrev_i32_e32 v33, 31, v32
	v_lshlrev_b64 v[124:125], 10, v[32:33]
	v_lshl_add_u64 v[124:125], v[124:125], 0, v[146:147]
	v_lshl_add_u64 v[160:161], v[124:125], 2, s[16:17]
	global_load_dwordx4 v[156:159], v[160:161], off offset:16
	global_load_dwordx4 v[166:169], v[160:161], off
	v_lshlrev_b64 v[170:171], 1, v[124:125]
	v_lshl_add_u64 v[124:125], s[26:27], 0, v[170:171]
	v_or_b32_e32 v170, 0x100, v170
	s_waitcnt vmcnt(1)
	v_pk_add_f32 v[26:27], v[26:27], v[158:159]
	s_waitcnt vmcnt(0)
	v_pk_add_f32 v[30:31], v[30:31], v[168:169]
	v_pk_add_f32 v[28:29], v[28:29], v[166:167]
	v_pk_add_f32 v[24:25], v[24:25], v[156:157]
	v_cvt_pk_bf16_f32 v156, v28, v29
	v_cvt_pk_bf16_f32 v157, v30, v31
	v_cvt_pk_bf16_f32 v158, v24, v25
	v_cvt_pk_bf16_f32 v159, v26, v27
	global_store_dwordx4 v[124:125], v[156:159], off
	global_load_dwordx4 v[156:159], v[160:161], off offset:528
	s_nop 0
	global_load_dwordx4 v[166:169], v[160:161], off offset:512
	s_waitcnt vmcnt(1)
	v_pk_add_f32 v[18:19], v[18:19], v[158:159]
	s_waitcnt vmcnt(0)
	v_pk_add_f32 v[22:23], v[22:23], v[168:169]
	v_pk_add_f32 v[124:125], v[20:21], v[166:167]
	v_pk_add_f32 v[20:21], v[16:17], v[156:157]
	v_cvt_pk_bf16_f32 v156, v124, v125
	v_cvt_pk_bf16_f32 v157, v22, v23
	v_cvt_pk_bf16_f32 v158, v20, v21
	v_cvt_pk_bf16_f32 v159, v18, v19
	v_lshl_add_u64 v[16:17], s[26:27], 0, v[170:171]
	global_store_dwordx4 v[16:17], v[156:159], off
	v_add_u32_e32 v16, 0xb0, v144
	v_ashrrev_i32_e32 v17, 31, v16
	v_lshlrev_b64 v[156:157], 10, v[16:17]
	v_lshl_add_u64 v[146:147], v[156:157], 0, v[146:147]
	v_lshl_add_u64 v[160:161], v[146:147], 2, s[16:17]
	global_load_dwordx4 v[156:159], v[160:161], off offset:16
	global_load_dwordx4 v[166:169], v[160:161], off
	v_lshlrev_b64 v[146:147], 1, v[146:147]
	s_waitcnt vmcnt(1)
	v_pk_add_f32 v[10:11], v[10:11], v[158:159]
	s_waitcnt vmcnt(0)
	v_pk_add_f32 v[14:15], v[14:15], v[168:169]
	v_pk_add_f32 v[12:13], v[12:13], v[166:167]
	v_pk_add_f32 v[8:9], v[8:9], v[156:157]
	v_cvt_pk_bf16_f32 v156, v12, v13
	v_cvt_pk_bf16_f32 v157, v14, v15
	v_cvt_pk_bf16_f32 v158, v8, v9
	v_cvt_pk_bf16_f32 v159, v10, v11
	v_lshl_add_u64 v[166:167], s[26:27], 0, v[146:147]
	global_store_dwordx4 v[166:167], v[156:159], off
	global_load_dwordx4 v[156:159], v[160:161], off offset:528
	s_nop 0
	global_load_dwordx4 v[166:169], v[160:161], off offset:512
	v_or_b32_e32 v146, 0x100, v146
	v_lshl_add_u64 v[146:147], s[26:27], 0, v[146:147]
	s_waitcnt vmcnt(1)
	v_pk_add_f32 v[2:3], v[2:3], v[158:159]
	s_waitcnt vmcnt(0)
	v_pk_add_f32 v[6:7], v[6:7], v[168:169]
	v_pk_add_f32 v[4:5], v[4:5], v[166:167]
	v_pk_add_f32 v[0:1], v[0:1], v[156:157]
	v_cvt_pk_bf16_f32 v156, v4, v5
	v_cvt_pk_bf16_f32 v157, v6, v7
	v_cvt_pk_bf16_f32 v158, v0, v1
	v_cvt_pk_bf16_f32 v159, v2, v3
	global_store_dwordx4 v[146:147], v[156:159], off
	v_mov_b32_e32 v146, v127
	v_mov_b32_e32 v250, v127
	s_nop 1
	v_permlane32_swap_b32_e32 v250, v146
	s_and_saveexec_b64 s[52:53], s[40:41]
	s_cbranch_execz .LBB0_696
; template <bool ISMAX> DI void tile_row_reduce(float (&p)[2][4], LAS float* red, int wr, int wc, int fr, int fq) {
;     ...
;         for (int m = 0; m < 4; ++m) { float v = p[ai][m]; const float a = __shfl_xor(v, 16); v = ISMAX ? fmaxf(v, a) : v + a; const float b = __shfl_xor(v, 32); v = ISMAX ? fmaxf(v, b) : v + b;
;             if (fq == 0) red[(ai * 128 + wr * 64 + m * 16 + fr) * 4 + wc] = v; }
;     DI void operator()(Acc& acc, const Unit& u, int wr, int wc, int fr, int fq, LAS unsigned char* lds) const {
;     ...
;                         ss += ((v0.x * v0.x + v0.y * v0.y) + (v0.z * v0.z + v0.w * v0.w)) + ((v1.x * v1.x + v1.y * v1.y) + (v1.z * v1.z + v1.w * v1.w)); } }
;                 part[ai][m] = ss; }
	s_waitcnt lgkmcnt(0)
	v_add_f32_e32 v127, v127, v146
	ds_write_b32 v126, v127
.LBB0_696:
	s_or_b64 exec, exec, s[52:53]
	v_mul_f32_e32 v105, v105, v105
	v_fmac_f32_e32 v105, v104, v104
	v_mul_f32_e32 v104, v107, v107
	v_mul_f32_e32 v109, v109, v109
	v_fmac_f32_e32 v104, v106, v106
	v_fmac_f32_e32 v109, v108, v108
	v_mul_f32_e32 v108, v111, v111
	v_add_f32_e32 v104, v105, v104
	v_mul_f32_e32 v105, v115, v115
	v_mul_f32_e32 v103, v103, v103
	v_mul_f32_e32 v101, v101, v101
	v_mul_f32_e32 v99, v99, v99
	v_fmac_f32_e32 v108, v110, v110
	v_fmac_f32_e32 v105, v114, v114
	v_fmac_f32_e32 v103, v102, v102
	v_fmac_f32_e32 v101, v100, v100
	v_fmac_f32_e32 v99, v98, v98
	v_add_f32_e32 v108, v109, v108
	v_add_f32_e32 v102, v105, v103
	v_add_f32_e32 v98, v101, v99
	v_add_f32_e32 v104, v108, v104
	v_add_f32_e32 v98, v102, v98
	v_add_f32_e32 v98, v104, v98
	v_mov_b32_e32 v99, v98
	v_mov_b32_e32 v250, v98
	s_nop 1
	v_permlane16_swap_b32_e32 v250, v99
	s_waitcnt lgkmcnt(0)
	v_add_f32_e32 v98, v250, v99
	v_mov_b32_e32 v99, v98
	v_mov_b32_e32 v250, v98
	s_nop 1
	v_permlane32_swap_b32_e32 v250, v99
	s_and_saveexec_b64 s[52:53], s[40:41]
	s_cbranch_execz .LBB0_698
	s_waitcnt lgkmcnt(0)
	v_add_f32_e32 v98, v98, v99
	ds_write_b32 v126, v98 offset:256
.LBB0_698:
	s_or_b64 exec, exec, s[52:53]
	v_mul_f32_e32 v89, v89, v89
	v_fmac_f32_e32 v89, v88, v88
	v_mul_f32_e32 v88, v91, v91
	v_mul_f32_e32 v93, v93, v93
	v_fmac_f32_e32 v88, v90, v90
	v_fmac_f32_e32 v93, v92, v92
	v_mul_f32_e32 v92, v95, v95
	v_add_f32_e32 v88, v89, v88
	v_mul_f32_e32 v89, v117, v117
	v_mul_f32_e32 v87, v87, v87
	v_mul_f32_e32 v85, v85, v85
	v_mul_f32_e32 v83, v83, v83
	v_fmac_f32_e32 v92, v94, v94
	v_fmac_f32_e32 v89, v116, v116
	v_fmac_f32_e32 v87, v86, v86
	v_fmac_f32_e32 v85, v84, v84
	v_fmac_f32_e32 v83, v82, v82
	v_add_f32_e32 v92, v93, v92
	v_add_f32_e32 v86, v89, v87
	v_add_f32_e32 v82, v85, v83
	v_add_f32_e32 v88, v92, v88
	v_add_f32_e32 v82, v86, v82
	v_add_f32_e32 v82, v88, v82
	v_mov_b32_e32 v83, v82
	v_mov_b32_e32 v250, v82
	s_nop 1
	v_permlane16_swap_b32_e32 v250, v83
	s_waitcnt lgkmcnt(0)
	v_add_f32_e32 v82, v250, v83
	v_mov_b32_e32 v83, v82
	v_mov_b32_e32 v250, v82
	s_nop 1
	v_permlane32_swap_b32_e32 v250, v83
	s_and_saveexec_b64 s[52:53], s[40:41]
	s_cbranch_execz .LBB0_700
	s_waitcnt lgkmcnt(0)
	v_add_f32_e32 v82, v82, v83
	ds_write_b32 v126, v82 offset:512
.LBB0_700:
	s_or_b64 exec, exec, s[52:53]
	v_mul_f32_e32 v73, v73, v73
	v_fmac_f32_e32 v73, v72, v72
	v_mul_f32_e32 v72, v75, v75
	v_mul_f32_e32 v77, v77, v77
	v_fmac_f32_e32 v72, v74, v74
	v_fmac_f32_e32 v77, v76, v76
	v_mul_f32_e32 v76, v79, v79
	v_add_f32_e32 v72, v73, v72
	v_mul_f32_e32 v73, v119, v119
	v_mul_f32_e32 v71, v71, v71
	v_mul_f32_e32 v69, v69, v69
	v_mul_f32_e32 v67, v67, v67
	v_fmac_f32_e32 v76, v78, v78
	v_fmac_f32_e32 v73, v118, v118
	v_fmac_f32_e32 v71, v70, v70
	v_fmac_f32_e32 v69, v68, v68
	v_fmac_f32_e32 v67, v66, v66
	v_add_f32_e32 v76, v77, v76
	v_add_f32_e32 v70, v73, v71
	v_add_f32_e32 v66, v69, v67
	v_add_f32_e32 v72, v76, v72
	v_add_f32_e32 v66, v70, v66
	v_add_f32_e32 v66, v72, v66
	v_mov_b32_e32 v67, v66
	v_mov_b32_e32 v250, v66
	s_nop 1
	v_permlane16_swap_b32_e32 v250, v67
	s_waitcnt lgkmcnt(0)
	v_add_f32_e32 v66, v250, v67
	v_mov_b32_e32 v67, v66
	v_mov_b32_e32 v250, v66
	s_nop 1
	v_permlane32_swap_b32_e32 v250, v67
	s_and_saveexec_b64 s[52:53], s[40:41]
	s_cbranch_execz .LBB0_702
	s_waitcnt lgkmcnt(0)
	v_add_f32_e32 v66, v66, v67
	ds_write_b32 v126, v66 offset:768
; template <bool ISMAX> DI void tile_row_reduce(float (&p)[2][4], LAS float* red, int wr, int wc, int fr, int fq) {
;     ...
;         for (int m = 0; m < 4; ++m) { float v = p[ai][m]; const float a = __shfl_xor(v, 16); v = ISMAX ? fmaxf(v, a) : v + a; const float b = __shfl_xor(v, 32); v = ISMAX ? fmaxf(v, b) : v + b;
;             if (fq == 0) red[(ai * 128 + wr * 64 + m * 16 + fr) * 4 + wc] = v; }
;     DI void operator()(Acc& acc, const Unit& u, int wr, int wc, int fr, int fq, LAS unsigned char* lds) const {
;     ...
;                         ss += ((v0.x * v0.x + v0.y * v0.y) + (v0.z * v0.z + v0.w * v0.w)) + ((v1.x * v1.x + v1.y * v1.y) + (v1.z * v1.z + v1.w * v1.w)); } }
;                 part[ai][m] = ss; }
.LBB0_702:
	s_or_b64 exec, exec, s[52:53]
	v_mul_f32_e32 v57, v57, v57
	v_fmac_f32_e32 v57, v56, v56
	v_mul_f32_e32 v56, v59, v59
	v_mul_f32_e32 v61, v61, v61
	v_fmac_f32_e32 v56, v58, v58
	v_fmac_f32_e32 v61, v60, v60
	v_mul_f32_e32 v60, v63, v63
	v_add_f32_e32 v56, v57, v56
	v_mul_f32_e32 v57, v121, v121
	v_mul_f32_e32 v55, v55, v55
	v_mul_f32_e32 v53, v53, v53
	v_mul_f32_e32 v51, v51, v51
	v_fmac_f32_e32 v60, v62, v62
	v_fmac_f32_e32 v57, v120, v120
	v_fmac_f32_e32 v55, v54, v54
	v_fmac_f32_e32 v53, v52, v52
	v_fmac_f32_e32 v51, v50, v50
	v_add_f32_e32 v60, v61, v60
	v_add_f32_e32 v54, v57, v55
	v_add_f32_e32 v50, v53, v51
	v_add_f32_e32 v56, v60, v56
	v_add_f32_e32 v50, v54, v50
	v_add_f32_e32 v50, v56, v50
	v_mov_b32_e32 v51, v50
	v_mov_b32_e32 v250, v50
	s_nop 1
	v_permlane16_swap_b32_e32 v250, v51
	s_waitcnt lgkmcnt(0)
	v_add_f32_e32 v50, v250, v51
	v_mov_b32_e32 v51, v50
	v_mov_b32_e32 v250, v50
	s_nop 1
	v_permlane32_swap_b32_e32 v250, v51
	s_and_saveexec_b64 s[52:53], s[40:41]
	s_cbranch_execz .LBB0_704
	s_waitcnt lgkmcnt(0)
	v_add_f32_e32 v50, v50, v51
	ds_write_b32 v126, v50 offset:2048
.LBB0_704:
	s_or_b64 exec, exec, s[52:53]
	v_mul_f32_e32 v41, v41, v41
	v_fmac_f32_e32 v41, v40, v40
	v_mul_f32_e32 v40, v43, v43
	v_mul_f32_e32 v45, v45, v45
	v_fmac_f32_e32 v40, v42, v42
	v_fmac_f32_e32 v45, v44, v44
	v_mul_f32_e32 v44, v47, v47
	v_add_f32_e32 v40, v41, v40
	v_mul_f32_e32 v41, v123, v123
	v_mul_f32_e32 v39, v39, v39
	v_mul_f32_e32 v37, v37, v37
	v_mul_f32_e32 v35, v35, v35
	v_fmac_f32_e32 v44, v46, v46
	v_fmac_f32_e32 v41, v122, v122
	v_fmac_f32_e32 v39, v38, v38
	v_fmac_f32_e32 v37, v36, v36
	v_fmac_f32_e32 v35, v34, v34
	v_add_f32_e32 v44, v45, v44
	v_add_f32_e32 v38, v41, v39
	v_add_f32_e32 v34, v37, v35
	v_add_f32_e32 v40, v44, v40
	v_add_f32_e32 v34, v38, v34
	v_add_f32_e32 v34, v40, v34
	v_mov_b32_e32 v35, v34
	v_mov_b32_e32 v250, v34
	s_nop 1
	v_permlane16_swap_b32_e32 v250, v35
	s_waitcnt lgkmcnt(0)
	v_add_f32_e32 v34, v250, v35
	v_mov_b32_e32 v35, v34
	v_mov_b32_e32 v250, v34
	s_nop 1
	v_permlane32_swap_b32_e32 v250, v35
	s_and_saveexec_b64 s[52:53], s[40:41]
	s_cbranch_execz .LBB0_706
	s_waitcnt lgkmcnt(0)
	v_add_f32_e32 v34, v34, v35
	ds_write_b32 v126, v34 offset:2304
.LBB0_706:
	s_or_b64 exec, exec, s[52:53]
	v_mul_f32_e32 v25, v25, v25
	v_fmac_f32_e32 v25, v24, v24
	v_mul_f32_e32 v24, v27, v27
	v_mul_f32_e32 v29, v29, v29
	v_fmac_f32_e32 v24, v26, v26
	v_fmac_f32_e32 v29, v28, v28
	v_mul_f32_e32 v28, v31, v31
	v_add_f32_e32 v24, v25, v24
	v_mul_f32_e32 v25, v125, v125
	v_mul_f32_e32 v23, v23, v23
	v_mul_f32_e32 v21, v21, v21
	v_mul_f32_e32 v19, v19, v19
	v_fmac_f32_e32 v28, v30, v30
	v_fmac_f32_e32 v25, v124, v124
	v_fmac_f32_e32 v23, v22, v22
	v_fmac_f32_e32 v21, v20, v20
	v_fmac_f32_e32 v19, v18, v18
	v_add_f32_e32 v28, v29, v28
	v_add_f32_e32 v22, v25, v23
	v_add_f32_e32 v18, v21, v19
	v_add_f32_e32 v24, v28, v24
	v_add_f32_e32 v18, v22, v18
	v_add_f32_e32 v18, v24, v18
	v_mov_b32_e32 v19, v18
	v_mov_b32_e32 v250, v18
	s_nop 1
	v_permlane16_swap_b32_e32 v250, v19
	s_waitcnt lgkmcnt(0)
	v_add_f32_e32 v18, v250, v19
	v_mov_b32_e32 v19, v18
	v_mov_b32_e32 v250, v18
	s_nop 1
	v_permlane32_swap_b32_e32 v250, v19
	s_and_saveexec_b64 s[52:53], s[40:41]
	s_cbranch_execz .LBB0_708
	s_waitcnt lgkmcnt(0)
	v_add_f32_e32 v18, v18, v19
	ds_write_b32 v126, v18 offset:2560
.LBB0_708:
	s_or_b64 exec, exec, s[52:53]
	v_mul_f32_e32 v13, v13, v13
	v_mul_f32_e32 v9, v9, v9
	v_mul_f32_e32 v5, v5, v5
	v_mul_f32_e32 v1, v1, v1
	v_fmac_f32_e32 v13, v12, v12
	v_mul_f32_e32 v12, v15, v15
	v_fmac_f32_e32 v9, v8, v8
	v_mul_f32_e32 v8, v11, v11
	v_fmac_f32_e32 v5, v4, v4
	v_mul_f32_e32 v4, v7, v7
	v_fmac_f32_e32 v1, v0, v0
	v_mul_f32_e32 v0, v3, v3
	v_fmac_f32_e32 v12, v14, v14
	v_fmac_f32_e32 v8, v10, v10
	v_fmac_f32_e32 v4, v6, v6
	v_fmac_f32_e32 v0, v2, v2
	v_add_f32_e32 v12, v13, v12
	v_add_f32_e32 v8, v9, v8
	v_add_f32_e32 v4, v5, v4
	v_add_f32_e32 v0, v1, v0
	v_add_f32_e32 v8, v12, v8
	v_add_f32_e32 v0, v4, v0
	v_add_f32_e32 v0, v8, v0
	v_mov_b32_e32 v1, v0
	v_mov_b32_e32 v250, v0
	s_nop 1
	v_permlane16_swap_b32_e32 v250, v1
	s_waitcnt lgkmcnt(0)
	v_add_f32_e32 v0, v250, v1
	v_mov_b32_e32 v1, v0
	v_mov_b32_e32 v250, v0
	s_nop 1
	v_permlane32_swap_b32_e32 v250, v1
	s_and_saveexec_b64 s[52:53], s[40:41]
	s_cbranch_execz .LBB0_710
	s_waitcnt lgkmcnt(0)
	v_add_f32_e32 v0, v0, v1
	ds_write_b32 v126, v0 offset:2816

; template <bool ISMAX> DI void tile_row_reduce(float (&p)[2][4], LAS float* red, int wr, int wc, int fr, int fq) {
;     ...
;         for (int m = 0; m < 4; ++m) { float v = p[ai][m]; const float a = __shfl_xor(v, 16); v = ISMAX ? fmaxf(v, a) : v + a; const float b = __shfl_xor(v, 32); v = ISMAX ? fmaxf(v, b) : v + b;
;             if (fq == 0) red[(ai * 128 + wr * 64 + m * 16 + fr) * 4 + wc] = v; }
;     DI void operator()(Acc& acc, const Unit& u, int wr, int wc, int fr, int fq, LAS unsigned char* lds) const {
;     ...
;             for (int m = 0; m < 4; ++m) { const int row = u.pm * BM + ai * HALF + wr * 64 + m * 16 + fr;
;                 float rs = 1.0f; if (sumsq) { const f32x4 q4 = *(const f32x4*)(sumsq + (size_t)row * 4); rs = rsqrtf(((q4.x + q4.y) + (q4.z + q4.w)) * (1.0f / DM) + EPS); } float ss = 0.f;
; #pragma unroll
;                 for (int bj = 0; bj < 2; ++bj)
; #pragma unroll
;                     for (int n = 0; n < 2; ++n) { const f32x4 v = acc[ai][bj][m][n] * rs; acc[ai][bj][m][n] = v; ss += (v.x * v.x + v.y * v.y) + (v.z * v.z + v.w * v.w); }
;                 part[ai][m] = ss; }
;         tile_row_reduce<false>(part, red, wr, wc, fr, fq);
.LBB0_798:
	v_pk_mul_f32 v[126:127], v[126:127], v[186:187] op_sel_hi:[1,0]
	v_pk_mul_f32 v[168:169], v[124:125], v[186:187] op_sel_hi:[1,0]
	v_mul_f32_e32 v125, v127, v127
	v_mul_f32_e32 v124, v169, v169
	v_fmac_f32_e32 v124, v168, v168
	v_fmac_f32_e32 v125, v126, v126
	v_add_f32_e32 v187, v124, v125
	v_pk_mul_f32 v[124:125], v[122:123], v[186:187] op_sel_hi:[1,0]
	v_pk_mul_f32 v[170:171], v[120:121], v[186:187] op_sel_hi:[1,0]
	v_mul_f32_e32 v121, v125, v125
	v_mul_f32_e32 v120, v171, v171
	v_fmac_f32_e32 v120, v170, v170
	v_fmac_f32_e32 v121, v124, v124
	v_add_f32_e32 v120, v120, v121
	v_add_f32_e32 v122, v187, v120
	v_pk_mul_f32 v[118:119], v[118:119], v[186:187] op_sel_hi:[1,0]
	v_pk_mul_f32 v[120:121], v[116:117], v[186:187] op_sel_hi:[1,0]
	v_mul_f32_e32 v117, v119, v119
	v_mul_f32_e32 v116, v121, v121
	v_fmac_f32_e32 v116, v120, v120
	v_fmac_f32_e32 v117, v118, v118
	v_add_f32_e32 v116, v116, v117
	v_add_f32_e32 v187, v116, v122
	v_pk_mul_f32 v[116:117], v[110:111], v[186:187] op_sel_hi:[1,0]
	v_pk_mul_f32 v[122:123], v[108:109], v[186:187] op_sel_hi:[1,0]
	v_mul_f32_e32 v109, v117, v117
	v_mul_f32_e32 v108, v123, v123
	v_fmac_f32_e32 v108, v122, v122
	v_fmac_f32_e32 v109, v116, v116
	v_add_f32_e32 v108, v108, v109
	v_add_f32_e32 v108, v108, v187
	v_mov_b32_e32 v109, v108
	v_mov_b32_e32 v250, v108
	s_nop 1
	v_permlane16_swap_b32_e32 v250, v109
	v_add_u32_e32 v186, s18, v177
	s_waitcnt lgkmcnt(0)
	v_add_f32_e32 v108, v250, v109
	v_mov_b32_e32 v109, v108
	v_mov_b32_e32 v250, v108
	s_nop 1
	v_permlane32_swap_b32_e32 v250, v109
	s_and_saveexec_b64 s[8:9], s[40:41]
	s_xor_b64 s[44:45], exec, s[8:9]
	s_cbranch_execz .LBB0_800
	s_waitcnt lgkmcnt(0)
	v_add_f32_e32 v108, v108, v109
	ds_write_b32 v186, v108
.LBB0_800:
	s_or_b64 exec, exec, s[44:45]
	s_waitcnt lgkmcnt(0)
	v_pk_mul_f32 v[108:109], v[114:115], v[182:183] op_sel_hi:[1,0]
	v_pk_mul_f32 v[112:113], v[112:113], v[182:183] op_sel_hi:[1,0]
	v_mul_f32_e32 v111, v109, v109
	v_mul_f32_e32 v110, v113, v113
	v_fmac_f32_e32 v110, v112, v112
	v_fmac_f32_e32 v111, v108, v108
	v_add_f32_e32 v187, v110, v111
	v_pk_mul_f32 v[110:111], v[106:107], v[182:183] op_sel_hi:[1,0]
	v_pk_mul_f32 v[114:115], v[104:105], v[182:183] op_sel_hi:[1,0]
	v_mul_f32_e32 v105, v111, v111
	v_mul_f32_e32 v104, v115, v115
	v_fmac_f32_e32 v104, v114, v114
	v_fmac_f32_e32 v105, v110, v110
	v_add_f32_e32 v104, v104, v105
	v_add_f32_e32 v106, v187, v104
	v_pk_mul_f32 v[102:103], v[102:103], v[182:183] op_sel_hi:[1,0]
	v_pk_mul_f32 v[104:105], v[100:101], v[182:183] op_sel_hi:[1,0]
	v_mul_f32_e32 v101, v103, v103
	v_mul_f32_e32 v100, v105, v105
	v_fmac_f32_e32 v100, v104, v104
	v_fmac_f32_e32 v101, v102, v102
	v_add_f32_e32 v100, v100, v101
	v_add_f32_e32 v187, v100, v106
	v_pk_mul_f32 v[100:101], v[94:95], v[182:183] op_sel_hi:[1,0]
	v_pk_mul_f32 v[106:107], v[92:93], v[182:183] op_sel_hi:[1,0]
	v_mul_f32_e32 v93, v101, v101
	v_mul_f32_e32 v92, v107, v107
	v_fmac_f32_e32 v92, v106, v106
	v_fmac_f32_e32 v93, v100, v100
	v_add_f32_e32 v92, v92, v93
	v_add_f32_e32 v92, v92, v187
	v_mov_b32_e32 v93, v92
	v_mov_b32_e32 v250, v92
	s_nop 1
	v_permlane16_swap_b32_e32 v250, v93
	s_waitcnt lgkmcnt(0)
	v_add_f32_e32 v92, v250, v93
	v_mov_b32_e32 v93, v92
	v_mov_b32_e32 v250, v92
	s_nop 1
	v_permlane32_swap_b32_e32 v250, v93
	s_and_saveexec_b64 s[44:45], s[40:41]
	s_cbranch_execz .LBB0_802
	s_waitcnt lgkmcnt(0)
	v_add_f32_e32 v92, v92, v93
	ds_write_b32 v186, v92 offset:256
.LBB0_802:
	s_or_b64 exec, exec, s[44:45]
	s_waitcnt lgkmcnt(0)
	v_pk_mul_f32 v[92:93], v[98:99], v[184:185] op_sel_hi:[1,0]
	v_pk_mul_f32 v[96:97], v[96:97], v[184:185] op_sel_hi:[1,0]
	v_mul_f32_e32 v95, v93, v93
	v_mul_f32_e32 v94, v97, v97
	v_fmac_f32_e32 v94, v96, v96
	v_fmac_f32_e32 v95, v92, v92
	v_add_f32_e32 v182, v94, v95
	v_pk_mul_f32 v[94:95], v[90:91], v[184:185] op_sel_hi:[1,0]
	v_pk_mul_f32 v[98:99], v[88:89], v[184:185] op_sel_hi:[1,0]
	v_mul_f32_e32 v89, v95, v95
	v_mul_f32_e32 v88, v99, v99
	v_fmac_f32_e32 v88, v98, v98
	v_fmac_f32_e32 v89, v94, v94
	v_add_f32_e32 v88, v88, v89
	v_add_f32_e32 v90, v182, v88
	v_pk_mul_f32 v[86:87], v[86:87], v[184:185] op_sel_hi:[1,0]
	v_pk_mul_f32 v[88:89], v[84:85], v[184:185] op_sel_hi:[1,0]
	v_mul_f32_e32 v85, v87, v87
	v_mul_f32_e32 v84, v89, v89
	v_fmac_f32_e32 v84, v88, v88
	v_fmac_f32_e32 v85, v86, v86
	v_add_f32_e32 v84, v84, v85
	v_add_f32_e32 v182, v84, v90
	v_pk_mul_f32 v[84:85], v[78:79], v[184:185] op_sel_hi:[1,0]
	v_pk_mul_f32 v[90:91], v[76:77], v[184:185] op_sel_hi:[1,0]
	v_mul_f32_e32 v77, v85, v85
	v_mul_f32_e32 v76, v91, v91
	v_fmac_f32_e32 v76, v90, v90
	v_fmac_f32_e32 v77, v84, v84
	v_add_f32_e32 v76, v76, v77
	v_add_f32_e32 v76, v76, v182
	v_mov_b32_e32 v77, v76
	v_mov_b32_e32 v250, v76
	s_nop 1
	v_permlane16_swap_b32_e32 v250, v77
	s_waitcnt lgkmcnt(0)
	v_add_f32_e32 v76, v250, v77
	v_mov_b32_e32 v77, v76
	v_mov_b32_e32 v250, v76
	s_nop 1
	v_permlane32_swap_b32_e32 v250, v77
	s_and_saveexec_b64 s[44:45], s[40:41]
	s_cbranch_execz .LBB0_804
	s_waitcnt lgkmcnt(0)
	v_add_f32_e32 v76, v76, v77
	ds_write_b32 v186, v76 offset:512
; template <bool ISMAX> DI void tile_row_reduce(float (&p)[2][4], LAS float* red, int wr, int wc, int fr, int fq) {
;     ...
;         for (int m = 0; m < 4; ++m) { float v = p[ai][m]; const float a = __shfl_xor(v, 16); v = ISMAX ? fmaxf(v, a) : v + a; const float b = __shfl_xor(v, 32); v = ISMAX ? fmaxf(v, b) : v + b;
;             if (fq == 0) red[(ai * 128 + wr * 64 + m * 16 + fr) * 4 + wc] = v; }
;     DI void operator()(Acc& acc, const Unit& u, int wr, int wc, int fr, int fq, LAS unsigned char* lds) const {
;     ...
;             for (int m = 0; m < 4; ++m) { const int row = u.pm * BM + ai * HALF + wr * 64 + m * 16 + fr;
;                 float rs = 1.0f; if (sumsq) { const f32x4 q4 = *(const f32x4*)(sumsq + (size_t)row * 4); rs = rsqrtf(((q4.x + q4.y) + (q4.z + q4.w)) * (1.0f / DM) + EPS); } float ss = 0.f;
; #pragma unroll
;                 for (int bj = 0; bj < 2; ++bj)
; #pragma unroll
;                     for (int n = 0; n < 2; ++n) { const f32x4 v = acc[ai][bj][m][n] * rs; acc[ai][bj][m][n] = v; ss += (v.x * v.x + v.y * v.y) + (v.z * v.z + v.w * v.w); }
;                 part[ai][m] = ss; }
;         tile_row_reduce<false>(part, red, wr, wc, fr, fq);
.LBB0_804:
	s_or_b64 exec, exec, s[44:45]
	s_waitcnt lgkmcnt(0)
	v_pk_mul_f32 v[76:77], v[82:83], v[178:179] op_sel_hi:[1,0]
	v_pk_mul_f32 v[80:81], v[80:81], v[178:179] op_sel_hi:[1,0]
	v_mul_f32_e32 v79, v77, v77
	v_mul_f32_e32 v78, v81, v81
	v_fmac_f32_e32 v78, v80, v80
	v_fmac_f32_e32 v79, v76, v76
	v_add_f32_e32 v182, v78, v79
	v_pk_mul_f32 v[78:79], v[74:75], v[178:179] op_sel_hi:[1,0]
	v_pk_mul_f32 v[82:83], v[72:73], v[178:179] op_sel_hi:[1,0]
	v_mul_f32_e32 v73, v79, v79
	v_mul_f32_e32 v72, v83, v83
	v_fmac_f32_e32 v72, v82, v82
	v_fmac_f32_e32 v73, v78, v78
	v_add_f32_e32 v72, v72, v73
	v_add_f32_e32 v74, v182, v72
	v_pk_mul_f32 v[70:71], v[70:71], v[178:179] op_sel_hi:[1,0]
	v_pk_mul_f32 v[72:73], v[68:69], v[178:179] op_sel_hi:[1,0]
	v_mul_f32_e32 v69, v71, v71
	v_mul_f32_e32 v68, v73, v73
	v_fmac_f32_e32 v68, v72, v72
	v_fmac_f32_e32 v69, v70, v70
	v_add_f32_e32 v68, v68, v69
	v_add_f32_e32 v182, v68, v74
	v_pk_mul_f32 v[68:69], v[66:67], v[178:179] op_sel_hi:[1,0]
	v_pk_mul_f32 v[74:75], v[64:65], v[178:179] op_sel_hi:[1,0]
	v_mul_f32_e32 v65, v69, v69
	v_mul_f32_e32 v64, v75, v75
	v_fmac_f32_e32 v64, v74, v74
	v_fmac_f32_e32 v65, v68, v68
	v_add_f32_e32 v64, v64, v65
	v_add_f32_e32 v64, v64, v182
	v_mov_b32_e32 v65, v64
	v_mov_b32_e32 v250, v64
	s_nop 1
	v_permlane16_swap_b32_e32 v250, v65
	s_waitcnt lgkmcnt(0)
	v_add_f32_e32 v64, v250, v65
	v_mov_b32_e32 v65, v64
	v_mov_b32_e32 v250, v64
	s_nop 1
	v_permlane32_swap_b32_e32 v250, v65
	s_and_saveexec_b64 s[44:45], s[40:41]
	s_cbranch_execz .LBB0_806
	s_waitcnt lgkmcnt(0)
	v_add_f32_e32 v64, v64, v65
	ds_write_b32 v186, v64 offset:768
.LBB0_806:
	s_or_b64 exec, exec, s[44:45]
	v_pk_mul_f32 v[62:63], v[62:63], v[180:181] op_sel_hi:[1,0]
	s_waitcnt lgkmcnt(0)
	v_pk_mul_f32 v[64:65], v[60:61], v[180:181] op_sel_hi:[1,0]
	v_mul_f32_e32 v61, v63, v63
	v_mul_f32_e32 v60, v65, v65
	v_fmac_f32_e32 v60, v64, v64
	v_fmac_f32_e32 v61, v62, v62
	v_add_f32_e32 v178, v60, v61
	v_pk_mul_f32 v[60:61], v[58:59], v[180:181] op_sel_hi:[1,0]
	v_pk_mul_f32 v[66:67], v[56:57], v[180:181] op_sel_hi:[1,0]
	v_mul_f32_e32 v57, v61, v61
	v_mul_f32_e32 v56, v67, v67
	v_fmac_f32_e32 v56, v66, v66
	v_fmac_f32_e32 v57, v60, v60
	v_add_f32_e32 v56, v56, v57
	v_add_f32_e32 v58, v178, v56
	v_pk_mul_f32 v[54:55], v[54:55], v[180:181] op_sel_hi:[1,0]
	v_pk_mul_f32 v[56:57], v[52:53], v[180:181] op_sel_hi:[1,0]
	v_mul_f32_e32 v53, v55, v55
	v_mul_f32_e32 v52, v57, v57
	v_fmac_f32_e32 v52, v56, v56
	v_fmac_f32_e32 v53, v54, v54
	v_add_f32_e32 v52, v52, v53
	v_add_f32_e32 v178, v52, v58
	v_pk_mul_f32 v[52:53], v[46:47], v[180:181] op_sel_hi:[1,0]
	v_pk_mul_f32 v[58:59], v[44:45], v[180:181] op_sel_hi:[1,0]
	v_mul_f32_e32 v45, v53, v53
	v_mul_f32_e32 v44, v59, v59
	v_fmac_f32_e32 v44, v58, v58
	v_fmac_f32_e32 v45, v52, v52
	v_add_f32_e32 v44, v44, v45
	v_add_f32_e32 v44, v44, v178
	v_mov_b32_e32 v45, v44
	v_mov_b32_e32 v250, v44
	s_nop 1
	v_permlane16_swap_b32_e32 v250, v45
	s_waitcnt lgkmcnt(0)
	v_add_f32_e32 v44, v250, v45
	v_mov_b32_e32 v45, v44
	v_mov_b32_e32 v250, v44
	s_nop 1
	v_permlane32_swap_b32_e32 v250, v45
	s_and_saveexec_b64 s[44:45], s[40:41]
	s_cbranch_execz .LBB0_808
	s_waitcnt lgkmcnt(0)
	v_add_f32_e32 v44, v44, v45
	ds_write_b32 v186, v44 offset:2048
; template <bool ISMAX> DI void tile_row_reduce(float (&p)[2][4], LAS float* red, int wr, int wc, int fr, int fq) {
;     ...
;         for (int m = 0; m < 4; ++m) { float v = p[ai][m]; const float a = __shfl_xor(v, 16); v = ISMAX ? fmaxf(v, a) : v + a; const float b = __shfl_xor(v, 32); v = ISMAX ? fmaxf(v, b) : v + b;
;             if (fq == 0) red[(ai * 128 + wr * 64 + m * 16 + fr) * 4 + wc] = v; }
;     DI void operator()(Acc& acc, const Unit& u, int wr, int wc, int fr, int fq, LAS unsigned char* lds) const {
;     ...
;             for (int m = 0; m < 4; ++m) { const int row = u.pm * BM + ai * HALF + wr * 64 + m * 16 + fr;
;                 float rs = 1.0f; if (sumsq) { const f32x4 q4 = *(const f32x4*)(sumsq + (size_t)row * 4); rs = rsqrtf(((q4.x + q4.y) + (q4.z + q4.w)) * (1.0f / DM) + EPS); } float ss = 0.f;
; #pragma unroll
;                 for (int bj = 0; bj < 2; ++bj)
; #pragma unroll
;                     for (int n = 0; n < 2; ++n) { const f32x4 v = acc[ai][bj][m][n] * rs; acc[ai][bj][m][n] = v; ss += (v.x * v.x + v.y * v.y) + (v.z * v.z + v.w * v.w); }
;                 part[ai][m] = ss; }
;         tile_row_reduce<false>(part, red, wr, wc, fr, fq);
.LBB0_808:
	s_or_b64 exec, exec, s[44:45]
	s_waitcnt lgkmcnt(0)
	v_pk_mul_f32 v[44:45], v[50:51], v[174:175] op_sel_hi:[1,0]
	v_pk_mul_f32 v[48:49], v[48:49], v[174:175] op_sel_hi:[1,0]
	v_mul_f32_e32 v47, v45, v45
	v_mul_f32_e32 v46, v49, v49
	v_fmac_f32_e32 v46, v48, v48
	v_fmac_f32_e32 v47, v44, v44
	v_add_f32_e32 v178, v46, v47
	v_pk_mul_f32 v[46:47], v[42:43], v[174:175] op_sel_hi:[1,0]
	v_pk_mul_f32 v[50:51], v[40:41], v[174:175] op_sel_hi:[1,0]
	v_mul_f32_e32 v41, v47, v47
	v_mul_f32_e32 v40, v51, v51
	v_fmac_f32_e32 v40, v50, v50
	v_fmac_f32_e32 v41, v46, v46
	v_add_f32_e32 v40, v40, v41
	v_add_f32_e32 v42, v178, v40
	v_pk_mul_f32 v[38:39], v[38:39], v[174:175] op_sel_hi:[1,0]
	v_pk_mul_f32 v[40:41], v[36:37], v[174:175] op_sel_hi:[1,0]
	v_mul_f32_e32 v37, v39, v39
	v_mul_f32_e32 v36, v41, v41
	v_fmac_f32_e32 v36, v40, v40
	v_fmac_f32_e32 v37, v38, v38
	v_add_f32_e32 v36, v36, v37
	v_add_f32_e32 v178, v36, v42
	v_pk_mul_f32 v[36:37], v[30:31], v[174:175] op_sel_hi:[1,0]
	v_pk_mul_f32 v[42:43], v[28:29], v[174:175] op_sel_hi:[1,0]
	v_mul_f32_e32 v29, v37, v37
	v_mul_f32_e32 v28, v43, v43
	v_fmac_f32_e32 v28, v42, v42
	v_fmac_f32_e32 v29, v36, v36
	v_add_f32_e32 v28, v28, v29
	v_add_f32_e32 v28, v28, v178
	v_mov_b32_e32 v29, v28
	v_mov_b32_e32 v250, v28
	s_nop 1
	v_permlane16_swap_b32_e32 v250, v29
	s_waitcnt lgkmcnt(0)
	v_add_f32_e32 v28, v250, v29
	v_mov_b32_e32 v29, v28
	v_mov_b32_e32 v250, v28
	s_nop 1
	v_permlane32_swap_b32_e32 v250, v29
	s_and_saveexec_b64 s[44:45], s[40:41]
	s_cbranch_execz .LBB0_810
	s_waitcnt lgkmcnt(0)
	v_add_f32_e32 v28, v28, v29
	ds_write_b32 v186, v28 offset:2304
.LBB0_810:
	s_or_b64 exec, exec, s[44:45]
	s_waitcnt lgkmcnt(0)
	v_pk_mul_f32 v[28:29], v[34:35], v[176:177] op_sel_hi:[1,0]
	v_pk_mul_f32 v[32:33], v[32:33], v[176:177] op_sel_hi:[1,0]
	v_mul_f32_e32 v31, v29, v29
	v_mul_f32_e32 v30, v33, v33
	v_fmac_f32_e32 v30, v32, v32
	v_fmac_f32_e32 v31, v28, v28
	v_add_f32_e32 v174, v30, v31
	v_pk_mul_f32 v[30:31], v[26:27], v[176:177] op_sel_hi:[1,0]
	v_pk_mul_f32 v[34:35], v[24:25], v[176:177] op_sel_hi:[1,0]
	v_mul_f32_e32 v25, v31, v31
	v_mul_f32_e32 v24, v35, v35
	v_fmac_f32_e32 v24, v34, v34
	v_fmac_f32_e32 v25, v30, v30
	v_add_f32_e32 v24, v24, v25
	v_add_f32_e32 v26, v174, v24
	v_pk_mul_f32 v[22:23], v[22:23], v[176:177] op_sel_hi:[1,0]
	v_pk_mul_f32 v[24:25], v[20:21], v[176:177] op_sel_hi:[1,0]
	v_mul_f32_e32 v21, v23, v23
	v_mul_f32_e32 v20, v25, v25
	v_fmac_f32_e32 v20, v24, v24
	v_fmac_f32_e32 v21, v22, v22
	v_add_f32_e32 v20, v20, v21
	v_add_f32_e32 v174, v20, v26
	v_pk_mul_f32 v[20:21], v[14:15], v[176:177] op_sel_hi:[1,0]
	v_pk_mul_f32 v[26:27], v[12:13], v[176:177] op_sel_hi:[1,0]
	v_mul_f32_e32 v13, v21, v21
	v_mul_f32_e32 v12, v27, v27
	v_fmac_f32_e32 v12, v26, v26
	v_fmac_f32_e32 v13, v20, v20
	v_add_f32_e32 v12, v12, v13
	v_add_f32_e32 v12, v12, v174
	v_mov_b32_e32 v13, v12
	v_mov_b32_e32 v250, v12
	s_nop 1
	v_permlane16_swap_b32_e32 v250, v13
	s_waitcnt lgkmcnt(0)
	v_add_f32_e32 v12, v250, v13
	v_mov_b32_e32 v13, v12
	v_mov_b32_e32 v250, v12
	s_nop 1
	v_permlane32_swap_b32_e32 v250, v13
	s_and_saveexec_b64 s[44:45], s[40:41]
	s_cbranch_execz .LBB0_812
	s_waitcnt lgkmcnt(0)
	v_add_f32_e32 v12, v12, v13
	ds_write_b32 v186, v12 offset:2560
.LBB0_812:
	s_or_b64 exec, exec, s[44:45]
	s_waitcnt lgkmcnt(0)
	v_pk_mul_f32 v[12:13], v[18:19], v[172:173] op_sel_hi:[1,0]
	v_pk_mul_f32 v[14:15], v[16:17], v[172:173] op_sel_hi:[1,0]
	v_mul_f32_e32 v17, v13, v13
	v_mul_f32_e32 v16, v15, v15
	v_fmac_f32_e32 v16, v14, v14
	v_fmac_f32_e32 v17, v12, v12
	v_pk_mul_f32 v[10:11], v[10:11], v[172:173] op_sel_hi:[1,0]
	v_pk_mul_f32 v[8:9], v[8:9], v[172:173] op_sel_hi:[1,0]
	v_add_f32_e32 v16, v16, v17
	v_mul_f32_e32 v17, v9, v9
	v_mul_f32_e32 v18, v11, v11
	v_fmac_f32_e32 v17, v8, v8
	v_fmac_f32_e32 v18, v10, v10
	v_add_f32_e32 v17, v17, v18
	v_pk_mul_f32 v[6:7], v[6:7], v[172:173] op_sel_hi:[1,0]
	v_pk_mul_f32 v[4:5], v[4:5], v[172:173] op_sel_hi:[1,0]
	v_add_f32_e32 v16, v16, v17
	v_mul_f32_e32 v17, v5, v5
	v_mul_f32_e32 v18, v7, v7
	v_fmac_f32_e32 v17, v4, v4
	v_fmac_f32_e32 v18, v6, v6
	v_add_f32_e32 v17, v17, v18
	v_pk_mul_f32 v[2:3], v[2:3], v[172:173] op_sel_hi:[1,0]
	v_pk_mul_f32 v[0:1], v[0:1], v[172:173] op_sel_hi:[1,0]
	v_add_f32_e32 v16, v17, v16
	v_mul_f32_e32 v17, v1, v1
	v_mul_f32_e32 v18, v3, v3
	v_fmac_f32_e32 v17, v0, v0
	v_fmac_f32_e32 v18, v2, v2
	v_add_f32_e32 v17, v17, v18
	v_add_f32_e32 v16, v17, v16
	v_mov_b32_e32 v17, v16
	v_mov_b32_e32 v250, v16
	s_nop 1
	v_permlane16_swap_b32_e32 v250, v17
	s_waitcnt lgkmcnt(0)
	v_add_f32_e32 v16, v250, v17
	v_mov_b32_e32 v17, v16
	v_mov_b32_e32 v250, v16
	s_nop 1
	v_permlane32_swap_b32_e32 v250, v17
	s_and_saveexec_b64 s[44:45], s[40:41]
	s_cbranch_execz .LBB0_814
	s_waitcnt lgkmcnt(0)
	v_add_f32_e32 v16, v16, v17
	ds_write_b32 v186, v16 offset:2816

; template <bool ISMAX> DI void tile_row_reduce(float (&p)[2][4], LAS float* red, int wr, int wc, int fr, int fq) {
;     ...
;         for (int m = 0; m < 4; ++m) { float v = p[ai][m]; const float a = __shfl_xor(v, 16); v = ISMAX ? fmaxf(v, a) : v + a; const float b = __shfl_xor(v, 32); v = ISMAX ? fmaxf(v, b) : v + b;
;             if (fq == 0) red[(ai * 128 + wr * 64 + m * 16 + fr) * 4 + wc] = v; }
;     DI void operator()(Acc& acc, const Unit& u, int wr, int wc, int fr, int fq, LAS unsigned char* lds) const {
;     ...
;             for (int m = 0; m < 4; ++m) { float mx = -3.0e38f;
; #pragma unroll
;                 for (int bj = 0; bj < 2; ++bj)
; #pragma unroll
;                     for (int n = 0; n < 2; ++n) { const f32x4 v = acc[ai][bj][m][n]; mx = fmaxf(mx, fmaxf(fmaxf(v.x, v.y), fmaxf(v.z, v.w))); }
;                 part[ai][m] = mx; }
;         tile_row_reduce<true>(part, red, wr, wc, fr, fq);
.LBB0_885:
	v_max_f32_e32 v128, v127, v127
	v_max_f32_e32 v129, v126, v126
	v_max_f32_e32 v128, v129, v128
	v_max_f32_e32 v129, v123, v123
	v_max_f32_e32 v130, v122, v122
	v_max_f32_e32 v129, v130, v129
	v_max3_f32 v128, v124, v125, v128
	v_max3_f32 v129, v120, v121, v129
	v_max3_f32 v128, v128, s87, v129
	v_max_f32_e32 v129, v119, v119
	v_max_f32_e32 v130, v118, v118
	v_max_f32_e32 v129, v130, v129
	v_max_f32_e32 v130, v115, v115
	v_max_f32_e32 v131, v114, v114
	v_max_f32_e32 v130, v131, v130
	v_max3_f32 v129, v116, v117, v129
	v_max3_f32 v130, v112, v113, v130
	v_max3_f32 v128, v128, v129, v130
	v_mov_b32_e32 v129, v128
	v_mov_b32_e32 v240, v128
	s_nop 1
	v_permlane16_swap_b32_e32 v240, v129
	s_waitcnt lgkmcnt(0)
	v_max_f32_e32 v129, v129, v129
	v_max_f32_e32 v129, v240, v129
	v_mov_b32_e32 v130, v129
	v_mov_b32_e32 v240, v129
	s_nop 1
	v_permlane32_swap_b32_e32 v240, v130
	v_add_u32_e32 v128, s18, v176
	s_and_saveexec_b64 s[52:53], s[40:41]
	s_cbranch_execz .LBB0_887
	s_waitcnt lgkmcnt(0)
	v_max_f32_e32 v130, v130, v130
	v_max_f32_e32 v129, v129, v129
	v_max_f32_e32 v129, v129, v130
	ds_write_b32 v128, v129
.LBB0_887:
	s_or_b64 exec, exec, s[52:53]
	v_max_f32_e32 v129, v111, v111
	s_waitcnt lgkmcnt(0)
	v_max_f32_e32 v130, v110, v110
	v_max_f32_e32 v129, v130, v129
	v_max_f32_e32 v130, v107, v107
	v_max_f32_e32 v131, v106, v106
	v_max_f32_e32 v130, v131, v130
	v_max3_f32 v129, v108, v109, v129
	v_max3_f32 v130, v104, v105, v130
	v_max3_f32 v129, v129, s87, v130
	v_max_f32_e32 v130, v103, v103
	v_max_f32_e32 v131, v102, v102
	v_max_f32_e32 v130, v131, v130
	v_max_f32_e32 v131, v99, v99
	v_max_f32_e32 v132, v98, v98
	v_max_f32_e32 v131, v132, v131
	v_max3_f32 v130, v100, v101, v130
	v_max3_f32 v131, v96, v97, v131
	v_max3_f32 v129, v129, v130, v131
	v_mov_b32_e32 v130, v129
	v_mov_b32_e32 v240, v129
	s_nop 1
	v_permlane16_swap_b32_e32 v240, v130
	s_waitcnt lgkmcnt(0)
	v_max_f32_e32 v130, v130, v130
	v_max_f32_e32 v129, v240, v130
	v_mov_b32_e32 v130, v129
	v_mov_b32_e32 v240, v129
	s_nop 1
	v_permlane32_swap_b32_e32 v240, v130
	s_and_saveexec_b64 s[52:53], s[40:41]
	s_cbranch_execz .LBB0_889
	s_waitcnt lgkmcnt(0)
	v_max_f32_e32 v130, v130, v130
	v_max_f32_e32 v129, v129, v129
	v_max_f32_e32 v129, v129, v130
	ds_write_b32 v128, v129 offset:256
.LBB0_889:
	s_or_b64 exec, exec, s[52:53]
	v_max_f32_e32 v129, v95, v95
	s_waitcnt lgkmcnt(0)
	v_max_f32_e32 v130, v94, v94
	v_max_f32_e32 v129, v130, v129
	v_max_f32_e32 v130, v91, v91
	v_max_f32_e32 v131, v90, v90
	v_max_f32_e32 v130, v131, v130
	v_max3_f32 v129, v92, v93, v129
	v_max3_f32 v130, v88, v89, v130
	v_max3_f32 v129, v129, s87, v130
	v_max_f32_e32 v130, v87, v87
	v_max_f32_e32 v131, v86, v86
	v_max_f32_e32 v130, v131, v130
	v_max_f32_e32 v131, v83, v83
	v_max_f32_e32 v132, v82, v82
	v_max_f32_e32 v131, v132, v131
	v_max3_f32 v130, v84, v85, v130
	v_max3_f32 v131, v80, v81, v131
	v_max3_f32 v129, v129, v130, v131
	v_mov_b32_e32 v130, v129
	v_mov_b32_e32 v240, v129
	s_nop 1
	v_permlane16_swap_b32_e32 v240, v130
	s_waitcnt lgkmcnt(0)
	v_max_f32_e32 v130, v130, v130
	v_max_f32_e32 v129, v240, v130
	v_mov_b32_e32 v130, v129
	v_mov_b32_e32 v240, v129
	s_nop 1
	v_permlane32_swap_b32_e32 v240, v130
	s_and_saveexec_b64 s[52:53], s[40:41]
	v_readlane_b32 s92, v253, 2
	v_readlane_b32 s93, v253, 3
	s_cbranch_execz .LBB0_891
	s_waitcnt lgkmcnt(0)
	v_max_f32_e32 v130, v130, v130
	v_max_f32_e32 v129, v129, v129
	v_max_f32_e32 v129, v129, v130
	ds_write_b32 v128, v129 offset:512
.LBB0_891:
	s_or_b64 exec, exec, s[52:53]
	v_max_f32_e32 v129, v79, v79
	s_waitcnt lgkmcnt(0)
	v_max_f32_e32 v130, v78, v78
	v_max_f32_e32 v129, v130, v129
	v_max_f32_e32 v130, v75, v75
	v_max_f32_e32 v131, v74, v74
	v_max_f32_e32 v130, v131, v130
	v_max3_f32 v129, v76, v77, v129
	v_max3_f32 v130, v72, v73, v130
	v_max3_f32 v129, v129, s87, v130
	v_max_f32_e32 v130, v71, v71
	v_max_f32_e32 v131, v70, v70
	v_max_f32_e32 v130, v131, v130
	v_max_f32_e32 v131, v67, v67
	v_max_f32_e32 v132, v66, v66
	v_max_f32_e32 v131, v132, v131
	v_max3_f32 v130, v68, v69, v130
	v_max3_f32 v131, v64, v65, v131
	v_max3_f32 v129, v129, v130, v131
	v_mov_b32_e32 v130, v129
	v_mov_b32_e32 v240, v129
	s_nop 1
	v_permlane16_swap_b32_e32 v240, v130
	s_waitcnt lgkmcnt(0)
	v_max_f32_e32 v130, v130, v130
	v_max_f32_e32 v129, v240, v130
	v_mov_b32_e32 v130, v129
	v_mov_b32_e32 v240, v129
	s_nop 1
	v_permlane32_swap_b32_e32 v240, v130
	s_and_saveexec_b64 s[52:53], s[40:41]
	s_cbranch_execz .LBB0_893
	s_waitcnt lgkmcnt(0)
	v_max_f32_e32 v130, v130, v130
	v_max_f32_e32 v129, v129, v129
	v_max_f32_e32 v129, v129, v130
	ds_write_b32 v128, v129 offset:768
.LBB0_893:
	s_or_b64 exec, exec, s[52:53]
	v_max_f32_e32 v129, v63, v63
	s_waitcnt lgkmcnt(0)
	v_max_f32_e32 v130, v62, v62
	v_max_f32_e32 v129, v130, v129
	v_max_f32_e32 v130, v59, v59
	v_max_f32_e32 v131, v58, v58
	v_max_f32_e32 v130, v131, v130
	v_max3_f32 v129, v60, v61, v129
	v_max3_f32 v130, v56, v57, v130
	v_max3_f32 v129, v129, s87, v130
	v_max_f32_e32 v130, v55, v55
	v_max_f32_e32 v131, v54, v54
	v_max_f32_e32 v130, v131, v130
	v_max_f32_e32 v131, v51, v51
	v_max_f32_e32 v132, v50, v50
	v_max_f32_e32 v131, v132, v131
	v_max3_f32 v130, v52, v53, v130
	v_max3_f32 v131, v48, v49, v131
	v_max3_f32 v129, v129, v130, v131
	v_mov_b32_e32 v130, v129
	v_mov_b32_e32 v240, v129
	s_nop 1
	v_permlane16_swap_b32_e32 v240, v130
	s_waitcnt lgkmcnt(0)
	v_max_f32_e32 v130, v130, v130
	v_max_f32_e32 v129, v240, v130
	v_mov_b32_e32 v130, v129
	v_mov_b32_e32 v240, v129
	s_nop 1
	v_permlane32_swap_b32_e32 v240, v130
	s_and_saveexec_b64 s[52:53], s[40:41]
	s_cbranch_execz .LBB0_895
	s_waitcnt lgkmcnt(0)
	v_max_f32_e32 v130, v130, v130
	v_max_f32_e32 v129, v129, v129
	v_max_f32_e32 v129, v129, v130
	ds_write_b32 v128, v129 offset:2048
; #define LAS __attribute__((address_space(3)))
; #define BAR_LDS() do { asm volatile("s_waitcnt lgkmcnt(0)" ::: "memory"); __builtin_amdgcn_s_barrier(); asm volatile("" ::: "memory"); } while (0)
; template <bool ISMAX> DI void tile_row_reduce(float (&p)[2][4], LAS float* red, int wr, int wc, int fr, int fq) {
;     ...
;         for (int m = 0; m < 4; ++m) { float v = p[ai][m]; const float a = __shfl_xor(v, 16); v = ISMAX ? fmaxf(v, a) : v + a; const float b = __shfl_xor(v, 32); v = ISMAX ? fmaxf(v, b) : v + b;
;             if (fq == 0) red[(ai * 128 + wr * 64 + m * 16 + fr) * 4 + wc] = v; }
;     BAR_LDS();
; #pragma unroll
;     for (int ai = 0; ai < 2; ++ai)
; #pragma unroll
;         for (int m = 0; m < 4; ++m) { const f32x4 q = *(const LAS f32x4*)(red + (ai * 128 + wr * 64 + m * 16 + fr) * 4);
;             p[ai][m] = ISMAX ? fmaxf(fmaxf(q.x, q.y), fmaxf(q.z, q.w)) : (q.x + q.y) + (q.z + q.w); }
;     DI void operator()(Acc& acc, const Unit& u, int wr, int wc, int fr, int fq, LAS unsigned char* lds) const {
;     ...
;         for (int ai = 0; ai < 2; ++ai)
; #pragma unroll
;             for (int m = 0; m < 4; ++m) { const float mx = part[ai][m] * LOG2E; float s = 0.f;
; #pragma unroll
;                 for (int bj = 0; bj < 2; ++bj)
; #pragma unroll
;                     for (int n = 0; n < 2; ++n) { f32x4 v = acc[ai][bj][m][n];
; #pragma unroll
;                         for (int e = 0; e < 4; ++e) { v[e] = __builtin_amdgcn_exp2f(v[e] * LOG2E - mx); s += v[e]; }
;                         acc[ai][bj][m][n] = v; }
;                 part2[ai][m] = s; }
.LBB0_895:
	s_or_b64 exec, exec, s[52:53]
	v_max_f32_e32 v129, v47, v47
	s_waitcnt lgkmcnt(0)
	v_max_f32_e32 v130, v46, v46
	v_max_f32_e32 v129, v130, v129
	v_max_f32_e32 v130, v43, v43
	v_max_f32_e32 v131, v42, v42
	v_max_f32_e32 v130, v131, v130
	v_max3_f32 v129, v44, v45, v129
	v_max3_f32 v130, v40, v41, v130
	v_max3_f32 v129, v129, s87, v130
	v_max_f32_e32 v130, v39, v39
	v_max_f32_e32 v131, v38, v38
	v_max_f32_e32 v130, v131, v130
	v_max_f32_e32 v131, v35, v35
	v_max_f32_e32 v132, v34, v34
	v_max_f32_e32 v131, v132, v131
	v_max3_f32 v130, v36, v37, v130
	v_max3_f32 v131, v32, v33, v131
	v_max3_f32 v129, v129, v130, v131
	v_mov_b32_e32 v130, v129
	v_mov_b32_e32 v240, v129
	s_nop 1
	v_permlane16_swap_b32_e32 v240, v130
	s_waitcnt lgkmcnt(0)
	v_max_f32_e32 v130, v130, v130
	v_max_f32_e32 v129, v240, v130
	v_mov_b32_e32 v130, v129
	v_mov_b32_e32 v240, v129
	s_nop 1
	v_permlane32_swap_b32_e32 v240, v130
	s_and_saveexec_b64 s[52:53], s[40:41]
	s_cbranch_execz .LBB0_897
	s_waitcnt lgkmcnt(0)
	v_max_f32_e32 v130, v130, v130
	v_max_f32_e32 v129, v129, v129
	v_max_f32_e32 v129, v129, v130
	ds_write_b32 v128, v129 offset:2304
.LBB0_897:
	s_or_b64 exec, exec, s[52:53]
	v_max_f32_e32 v129, v31, v31
	s_waitcnt lgkmcnt(0)
	v_max_f32_e32 v130, v30, v30
	v_max_f32_e32 v129, v130, v129
	v_max_f32_e32 v130, v27, v27
	v_max_f32_e32 v131, v26, v26
	v_max_f32_e32 v130, v131, v130
	v_max3_f32 v129, v28, v29, v129
	v_max3_f32 v130, v24, v25, v130
	v_max3_f32 v129, v129, s87, v130
	v_max_f32_e32 v130, v23, v23
	v_max_f32_e32 v131, v22, v22
	v_max_f32_e32 v130, v131, v130
	v_max_f32_e32 v131, v19, v19
	v_max_f32_e32 v132, v18, v18
	v_max_f32_e32 v131, v132, v131
	v_max3_f32 v130, v20, v21, v130
	v_max3_f32 v131, v16, v17, v131
	v_max3_f32 v129, v129, v130, v131
	v_mov_b32_e32 v130, v129
	v_mov_b32_e32 v240, v129
	s_nop 1
	v_permlane16_swap_b32_e32 v240, v130
	s_waitcnt lgkmcnt(0)
	v_max_f32_e32 v130, v130, v130
	v_max_f32_e32 v129, v240, v130
	v_mov_b32_e32 v130, v129
	v_mov_b32_e32 v240, v129
	s_nop 1
	v_permlane32_swap_b32_e32 v240, v130
	s_and_saveexec_b64 s[52:53], s[40:41]
	s_cbranch_execz .LBB0_899
	s_waitcnt lgkmcnt(0)
	v_max_f32_e32 v130, v130, v130
	v_max_f32_e32 v129, v129, v129
	v_max_f32_e32 v129, v129, v130
	ds_write_b32 v128, v129 offset:2560
.LBB0_899:
	s_or_b64 exec, exec, s[52:53]
	v_max_f32_e32 v129, v15, v15
	s_waitcnt lgkmcnt(0)
	v_max_f32_e32 v130, v14, v14
	v_max_f32_e32 v129, v130, v129
	v_max_f32_e32 v130, v11, v11
	v_max_f32_e32 v131, v10, v10
	v_max_f32_e32 v130, v131, v130
	v_max3_f32 v129, v12, v13, v129
	v_max3_f32 v130, v8, v9, v130
	v_max3_f32 v129, v129, s87, v130
	v_max_f32_e32 v130, v7, v7
	v_max_f32_e32 v131, v6, v6
	v_max_f32_e32 v130, v131, v130
	v_max_f32_e32 v131, v3, v3
	v_max_f32_e32 v132, v2, v2
	v_max_f32_e32 v131, v132, v131
	v_max3_f32 v130, v4, v5, v130
	v_max3_f32 v131, v0, v1, v131
	v_max3_f32 v129, v129, v130, v131
	v_mov_b32_e32 v130, v129
	v_mov_b32_e32 v240, v129
	s_nop 1
	v_permlane16_swap_b32_e32 v240, v130
	s_waitcnt lgkmcnt(0)
	v_max_f32_e32 v130, v130, v130
	v_max_f32_e32 v129, v240, v130
	v_mov_b32_e32 v130, v129
	v_mov_b32_e32 v240, v129
	s_nop 1
	v_permlane32_swap_b32_e32 v240, v130
	s_and_saveexec_b64 s[52:53], s[40:41]
	s_cbranch_execz .LBB0_901
	s_waitcnt lgkmcnt(0)
	v_max_f32_e32 v130, v130, v130
	v_max_f32_e32 v129, v129, v129
	v_max_f32_e32 v129, v129, v130
	ds_write_b32 v128, v129 offset:2816
.LBB0_901:
	s_or_b64 exec, exec, s[52:53]
	s_waitcnt lgkmcnt(0)
	s_barrier
	v_add_u32_e32 v128, s13, v176
	s_waitcnt lgkmcnt(0)
	ds_read_b128 v[128:131], v128
	v_add_u32_e32 v132, s35, v176
	ds_read_b128 v[144:147], v132
	v_mov_b32_e32 v166, v115
	s_waitcnt lgkmcnt(0)
	v_max_f32_e32 v131, v131, v131
	v_max_f32_e32 v130, v130, v130
	v_max_f32_e32 v130, v130, v131
	v_max3_f32 v167, v128, v129, v130
	v_pk_mul_f32 v[180:181], v[166:167], s[34:35] op_sel_hi:[1,0]
	v_add_u32_e32 v128, s36, v176
	v_fma_f32 v115, v124, s34, -v181
	v_exp_f32_e32 v124, v115
	v_fma_f32 v115, v125, s34, -v181
	v_exp_f32_e32 v125, v115
	v_fma_f32 v115, v126, s34, -v181
	v_exp_f32_e32 v166, v115
	v_fma_f32 v115, v127, s34, -v181
	v_exp_f32_e32 v167, v115
	v_fma_f32 v120, v120, s34, -v181
	v_add_f32_e32 v115, 0, v124
	v_exp_f32_e32 v126, v120
	v_fma_f32 v120, v121, s34, -v181
	v_add_f32_e32 v115, v125, v115
	v_exp_f32_e32 v127, v120
	v_fma_f32 v120, v122, s34, -v181
	v_add_f32_e32 v115, v166, v115
	v_exp_f32_e32 v170, v120
	v_fma_f32 v120, v123, s34, -v181
	v_add_f32_e32 v115, v167, v115
	v_exp_f32_e32 v171, v120
	v_fma_f32 v116, v116, s34, -v181
	v_add_f32_e32 v115, v126, v115
	v_exp_f32_e32 v120, v116
	v_fma_f32 v116, v117, s34, -v181
	v_add_f32_e32 v115, v127, v115
	v_exp_f32_e32 v121, v116
	v_fma_f32 v116, v118, s34, -v181
	v_add_f32_e32 v115, v170, v115
	v_exp_f32_e32 v168, v116
	v_fma_f32 v116, v119, s34, -v181
	v_add_f32_e32 v115, v171, v115
	v_exp_f32_e32 v169, v116
	v_fma_f32 v112, v112, s34, -v181
	v_add_f32_e32 v115, v120, v115
	v_exp_f32_e32 v122, v112
	v_fma_f32 v112, v113, s34, -v181
	v_add_f32_e32 v115, v121, v115
	v_exp_f32_e32 v123, v112
	v_fma_f32 v112, v114, s34, -v181
	v_add_f32_e32 v115, v168, v115
	v_exp_f32_e32 v172, v112
	v_sub_f32_e32 v112, v180, v181
	v_add_f32_e32 v115, v169, v115
	v_exp_f32_e32 v173, v112
	v_add_f32_e32 v112, v122, v115
	v_add_f32_e32 v112, v123, v112
	v_add_f32_e32 v112, v172, v112
	v_add_f32_e32 v180, v173, v112
	v_mov_b32_e32 v181, v180
	v_mov_b32_e32 v240, v180
	s_nop 1
	v_permlane16_swap_b32_e32 v240, v181
	v_add_u32_e32 v129, s37, v176
	ds_read_b128 v[140:143], v128
	ds_read_b128 v[136:139], v129
	v_add_u32_e32 v128, s70, v176
	v_add_u32_e32 v129, s71, v176
	v_add_u32_e32 v112, s72, v176
	v_add_u32_e32 v113, s73, v176
	s_waitcnt lgkmcnt(0)
	v_add_f32_e32 v181, v240, v181
	ds_read_b128 v[132:135], v128
	ds_read_b128 v[128:131], v129
	ds_read_b128 v[116:119], v112
	ds_read_b128 v[112:115], v113
	v_mov_b32_e32 v182, v181
	v_mov_b32_e32 v240, v181
	s_nop 1
	v_permlane32_swap_b32_e32 v240, v182
	v_add_u32_e32 v180, s33, v176
	s_and_saveexec_b64 s[52:53], s[40:41]
	s_cbranch_execz .LBB0_903
	s_waitcnt lgkmcnt(0)
	v_add_f32_e32 v181, v181, v182
	ds_write_b32 v180, v181
; template <bool ISMAX> DI void tile_row_reduce(float (&p)[2][4], LAS float* red, int wr, int wc, int fr, int fq) {
;     ...
;         for (int m = 0; m < 4; ++m) { float v = p[ai][m]; const float a = __shfl_xor(v, 16); v = ISMAX ? fmaxf(v, a) : v + a; const float b = __shfl_xor(v, 32); v = ISMAX ? fmaxf(v, b) : v + b;
;             if (fq == 0) red[(ai * 128 + wr * 64 + m * 16 + fr) * 4 + wc] = v; }
;     DI void operator()(Acc& acc, const Unit& u, int wr, int wc, int fr, int fq, LAS unsigned char* lds) const {
;     ...
;         for (int ai = 0; ai < 2; ++ai)
; #pragma unroll
;             for (int m = 0; m < 4; ++m) { const float mx = part[ai][m] * LOG2E; float s = 0.f;
; #pragma unroll
;                 for (int bj = 0; bj < 2; ++bj)
; #pragma unroll
;                     for (int n = 0; n < 2; ++n) { f32x4 v = acc[ai][bj][m][n];
; #pragma unroll
;                         for (int e = 0; e < 4; ++e) { v[e] = __builtin_amdgcn_exp2f(v[e] * LOG2E - mx); s += v[e]; }
;                         acc[ai][bj][m][n] = v; }
;                 part2[ai][m] = s; }
;         tile_row_reduce<false>(part2, red + 1024, wr, wc, fr, fq);
.LBB0_903:
	s_or_b64 exec, exec, s[52:53]
	v_max_f32_e32 v147, v147, v147
	v_max_f32_e32 v146, v146, v146
	v_max_f32_e32 v146, v146, v147
	v_max3_f32 v145, v144, v145, v146
	v_mov_b32_e32 v144, v99
	v_pk_mul_f32 v[144:145], v[144:145], s[34:35] op_sel_hi:[1,0]
	s_nop 0
	v_fma_f32 v99, v108, s34, -v145
	v_exp_f32_e32 v108, v99
	v_fma_f32 v99, v109, s34, -v145
	v_exp_f32_e32 v109, v99
	v_fma_f32 v99, v110, s34, -v145
	v_exp_f32_e32 v110, v99
	v_fma_f32 v99, v111, s34, -v145
	v_exp_f32_e32 v111, v99
	v_fma_f32 v104, v104, s34, -v145
	v_add_f32_e32 v99, 0, v108
	v_exp_f32_e32 v104, v104
	v_fma_f32 v105, v105, s34, -v145
	v_add_f32_e32 v99, v109, v99
	v_exp_f32_e32 v105, v105
	v_fma_f32 v106, v106, s34, -v145
	v_add_f32_e32 v99, v110, v99
	v_exp_f32_e32 v106, v106
	v_fma_f32 v107, v107, s34, -v145
	v_add_f32_e32 v99, v111, v99
	v_exp_f32_e32 v107, v107
	v_fma_f32 v100, v100, s34, -v145
	v_add_f32_e32 v99, v104, v99
	v_exp_f32_e32 v100, v100
	v_fma_f32 v101, v101, s34, -v145
	v_add_f32_e32 v99, v105, v99
	v_exp_f32_e32 v101, v101
	v_fma_f32 v102, v102, s34, -v145
	v_add_f32_e32 v99, v106, v99
	v_exp_f32_e32 v102, v102
	v_fma_f32 v103, v103, s34, -v145
	v_add_f32_e32 v99, v107, v99
	v_exp_f32_e32 v103, v103
	v_add_f32_e32 v99, v100, v99
	v_fma_f32 v96, v96, s34, -v145
	v_add_f32_e32 v99, v101, v99
	v_exp_f32_e32 v96, v96
	v_fma_f32 v97, v97, s34, -v145
	v_add_f32_e32 v99, v102, v99
	v_exp_f32_e32 v97, v97
	v_fma_f32 v98, v98, s34, -v145
	v_add_f32_e32 v146, v103, v99
	v_exp_f32_e32 v98, v98
	v_sub_f32_e32 v99, v144, v145
	v_exp_f32_e32 v99, v99
	v_add_f32_e32 v144, v96, v146
	v_add_f32_e32 v144, v97, v144
	v_add_f32_e32 v144, v98, v144
	v_add_f32_e32 v144, v99, v144
	v_mov_b32_e32 v145, v144
	v_mov_b32_e32 v240, v144
	s_nop 1
	v_permlane16_swap_b32_e32 v240, v145
	s_waitcnt lgkmcnt(0)
	v_add_f32_e32 v144, v240, v145
	v_mov_b32_e32 v145, v144
	v_mov_b32_e32 v240, v144
	s_nop 1
	v_permlane32_swap_b32_e32 v240, v145
	s_and_saveexec_b64 s[52:53], s[40:41]
	s_cbranch_execz .LBB0_905
	s_waitcnt lgkmcnt(0)
	v_add_f32_e32 v144, v144, v145
	ds_write_b32 v180, v144 offset:256
.LBB0_905:
	s_or_b64 exec, exec, s[52:53]
	v_max_f32_e32 v143, v143, v143
	v_max_f32_e32 v142, v142, v142
	v_max_f32_e32 v142, v142, v143
	v_max3_f32 v141, v140, v141, v142
	v_mov_b32_e32 v140, v83
	v_pk_mul_f32 v[140:141], v[140:141], s[34:35] op_sel_hi:[1,0]
	s_nop 0
	v_fma_f32 v83, v92, s34, -v141
	v_exp_f32_e32 v92, v83
	v_fma_f32 v83, v93, s34, -v141
	v_exp_f32_e32 v93, v83
	v_fma_f32 v83, v94, s34, -v141
	v_exp_f32_e32 v94, v83
	v_fma_f32 v83, v95, s34, -v141
	v_exp_f32_e32 v95, v83
	v_fma_f32 v88, v88, s34, -v141
	v_add_f32_e32 v83, 0, v92
	v_exp_f32_e32 v88, v88
	v_fma_f32 v89, v89, s34, -v141
	v_add_f32_e32 v83, v93, v83
	v_exp_f32_e32 v89, v89
	v_fma_f32 v90, v90, s34, -v141
	v_add_f32_e32 v83, v94, v83
	v_exp_f32_e32 v90, v90
	v_fma_f32 v91, v91, s34, -v141
	v_add_f32_e32 v83, v95, v83
	v_exp_f32_e32 v91, v91
	v_fma_f32 v84, v84, s34, -v141
	v_add_f32_e32 v83, v88, v83
	v_exp_f32_e32 v84, v84
	v_fma_f32 v85, v85, s34, -v141
	v_add_f32_e32 v83, v89, v83
	v_exp_f32_e32 v85, v85
	v_fma_f32 v86, v86, s34, -v141
	v_add_f32_e32 v83, v90, v83
	v_exp_f32_e32 v86, v86
	v_fma_f32 v87, v87, s34, -v141
	v_add_f32_e32 v83, v91, v83
	v_exp_f32_e32 v87, v87
	v_add_f32_e32 v83, v84, v83
	v_fma_f32 v80, v80, s34, -v141
	v_add_f32_e32 v83, v85, v83
	v_exp_f32_e32 v80, v80
	v_fma_f32 v81, v81, s34, -v141
	v_add_f32_e32 v83, v86, v83
	v_exp_f32_e32 v81, v81
	v_fma_f32 v82, v82, s34, -v141
	v_add_f32_e32 v142, v87, v83
	v_exp_f32_e32 v82, v82
	v_sub_f32_e32 v83, v140, v141
	v_exp_f32_e32 v83, v83
	v_add_f32_e32 v140, v80, v142
	v_add_f32_e32 v140, v81, v140
	v_add_f32_e32 v140, v82, v140
	v_add_f32_e32 v140, v83, v140
	v_mov_b32_e32 v141, v140
	v_mov_b32_e32 v240, v140
	s_nop 1
	v_permlane16_swap_b32_e32 v240, v141
	s_waitcnt lgkmcnt(0)
	v_add_f32_e32 v140, v240, v141
	v_mov_b32_e32 v141, v140
	v_mov_b32_e32 v240, v140
	s_nop 1
	v_permlane32_swap_b32_e32 v240, v141
	s_and_saveexec_b64 s[52:53], s[40:41]
	s_cbranch_execz .LBB0_907
	s_waitcnt lgkmcnt(0)
	v_add_f32_e32 v140, v140, v141
	ds_write_b32 v180, v140 offset:512
.LBB0_907:
	s_or_b64 exec, exec, s[52:53]
	v_max_f32_e32 v139, v139, v139
	v_max_f32_e32 v138, v138, v138
	v_max_f32_e32 v138, v138, v139
	v_max3_f32 v137, v136, v137, v138
	v_mov_b32_e32 v136, v67
	v_pk_mul_f32 v[136:137], v[136:137], s[34:35] op_sel_hi:[1,0]
	s_nop 0
	v_fma_f32 v67, v76, s34, -v137
	v_exp_f32_e32 v76, v67
	v_fma_f32 v67, v77, s34, -v137
	v_exp_f32_e32 v77, v67
	v_fma_f32 v67, v78, s34, -v137
	v_exp_f32_e32 v78, v67
	v_fma_f32 v67, v79, s34, -v137
	v_exp_f32_e32 v79, v67
	v_fma_f32 v72, v72, s34, -v137
	v_add_f32_e32 v67, 0, v76
	v_exp_f32_e32 v72, v72
	v_fma_f32 v73, v73, s34, -v137
	v_add_f32_e32 v67, v77, v67
	v_exp_f32_e32 v73, v73
	v_fma_f32 v74, v74, s34, -v137
	v_add_f32_e32 v67, v78, v67
	v_exp_f32_e32 v74, v74
	v_fma_f32 v75, v75, s34, -v137
	v_add_f32_e32 v67, v79, v67
	v_exp_f32_e32 v75, v75
	v_fma_f32 v68, v68, s34, -v137
	v_add_f32_e32 v67, v72, v67
	v_exp_f32_e32 v68, v68
	v_fma_f32 v69, v69, s34, -v137
	v_add_f32_e32 v67, v73, v67
	v_exp_f32_e32 v69, v69
	v_fma_f32 v70, v70, s34, -v137
	v_add_f32_e32 v67, v74, v67
	v_exp_f32_e32 v70, v70
	v_fma_f32 v71, v71, s34, -v137
	v_add_f32_e32 v67, v75, v67
	v_exp_f32_e32 v71, v71
	v_add_f32_e32 v67, v68, v67
	v_fma_f32 v64, v64, s34, -v137
	v_add_f32_e32 v67, v69, v67
	v_exp_f32_e32 v64, v64
	v_fma_f32 v65, v65, s34, -v137
	v_add_f32_e32 v67, v70, v67
	v_exp_f32_e32 v65, v65
	v_fma_f32 v66, v66, s34, -v137
	v_add_f32_e32 v138, v71, v67
	v_exp_f32_e32 v66, v66
	v_sub_f32_e32 v67, v136, v137
	v_exp_f32_e32 v67, v67
	v_add_f32_e32 v136, v64, v138
	v_add_f32_e32 v136, v65, v136
	v_add_f32_e32 v136, v66, v136
	v_add_f32_e32 v136, v67, v136
	v_mov_b32_e32 v137, v136
	v_mov_b32_e32 v240, v136
	s_nop 1
	v_permlane16_swap_b32_e32 v240, v137
	s_waitcnt lgkmcnt(0)
	v_add_f32_e32 v136, v240, v137
	v_mov_b32_e32 v137, v136
	v_mov_b32_e32 v240, v136
	s_nop 1
	v_permlane32_swap_b32_e32 v240, v137
	s_and_saveexec_b64 s[52:53], s[40:41]
	s_cbranch_execz .LBB0_909
	s_waitcnt lgkmcnt(0)
	v_add_f32_e32 v136, v136, v137
	ds_write_b32 v180, v136 offset:768
; template <bool ISMAX> DI void tile_row_reduce(float (&p)[2][4], LAS float* red, int wr, int wc, int fr, int fq) {
;     ...
;         for (int m = 0; m < 4; ++m) { float v = p[ai][m]; const float a = __shfl_xor(v, 16); v = ISMAX ? fmaxf(v, a) : v + a; const float b = __shfl_xor(v, 32); v = ISMAX ? fmaxf(v, b) : v + b;
;             if (fq == 0) red[(ai * 128 + wr * 64 + m * 16 + fr) * 4 + wc] = v; }
;     DI void operator()(Acc& acc, const Unit& u, int wr, int wc, int fr, int fq, LAS unsigned char* lds) const {
;     ...
;         for (int ai = 0; ai < 2; ++ai)
; #pragma unroll
;             for (int m = 0; m < 4; ++m) { const float mx = part[ai][m] * LOG2E; float s = 0.f;
; #pragma unroll
;                 for (int bj = 0; bj < 2; ++bj)
; #pragma unroll
;                     for (int n = 0; n < 2; ++n) { f32x4 v = acc[ai][bj][m][n];
; #pragma unroll
;                         for (int e = 0; e < 4; ++e) { v[e] = __builtin_amdgcn_exp2f(v[e] * LOG2E - mx); s += v[e]; }
;                         acc[ai][bj][m][n] = v; }
;                 part2[ai][m] = s; }
;         tile_row_reduce<false>(part2, red + 1024, wr, wc, fr, fq);
.LBB0_909:
	s_or_b64 exec, exec, s[52:53]
	v_max_f32_e32 v135, v135, v135
	v_max_f32_e32 v134, v134, v134
	v_max_f32_e32 v134, v134, v135
	v_max3_f32 v133, v132, v133, v134
	v_mov_b32_e32 v132, v51
	v_pk_mul_f32 v[132:133], v[132:133], s[34:35] op_sel_hi:[1,0]
	s_nop 0
	v_fma_f32 v51, v60, s34, -v133
	v_exp_f32_e32 v60, v51
	v_fma_f32 v51, v61, s34, -v133
	v_exp_f32_e32 v61, v51
	v_fma_f32 v51, v62, s34, -v133
	v_exp_f32_e32 v62, v51
	v_fma_f32 v51, v63, s34, -v133
	v_exp_f32_e32 v63, v51
	v_fma_f32 v56, v56, s34, -v133
	v_add_f32_e32 v51, 0, v60
	v_exp_f32_e32 v56, v56
	v_fma_f32 v57, v57, s34, -v133
	v_add_f32_e32 v51, v61, v51
	v_exp_f32_e32 v57, v57
	v_fma_f32 v58, v58, s34, -v133
	v_add_f32_e32 v51, v62, v51
	v_exp_f32_e32 v58, v58
	v_fma_f32 v59, v59, s34, -v133
	v_add_f32_e32 v51, v63, v51
	v_exp_f32_e32 v59, v59
	v_fma_f32 v52, v52, s34, -v133
	v_add_f32_e32 v51, v56, v51
	v_exp_f32_e32 v52, v52
	v_fma_f32 v53, v53, s34, -v133
	v_add_f32_e32 v51, v57, v51
	v_exp_f32_e32 v53, v53
	v_fma_f32 v54, v54, s34, -v133
	v_add_f32_e32 v51, v58, v51
	v_exp_f32_e32 v54, v54
	v_fma_f32 v55, v55, s34, -v133
	v_add_f32_e32 v51, v59, v51
	v_exp_f32_e32 v55, v55
	v_add_f32_e32 v51, v52, v51
	v_fma_f32 v48, v48, s34, -v133
	v_add_f32_e32 v51, v53, v51
	v_exp_f32_e32 v48, v48
	v_fma_f32 v49, v49, s34, -v133
	v_add_f32_e32 v51, v54, v51
	v_exp_f32_e32 v49, v49
	v_fma_f32 v50, v50, s34, -v133
	v_add_f32_e32 v134, v55, v51
	v_exp_f32_e32 v50, v50
	v_sub_f32_e32 v51, v132, v133
	v_exp_f32_e32 v51, v51
	v_add_f32_e32 v132, v48, v134
	v_add_f32_e32 v132, v49, v132
	v_add_f32_e32 v132, v50, v132
	v_add_f32_e32 v132, v51, v132
	v_mov_b32_e32 v133, v132
	v_mov_b32_e32 v240, v132
	s_nop 1
	v_permlane16_swap_b32_e32 v240, v133
	s_waitcnt lgkmcnt(0)
	v_add_f32_e32 v132, v240, v133
	v_mov_b32_e32 v133, v132
	v_mov_b32_e32 v240, v132
	s_nop 1
	v_permlane32_swap_b32_e32 v240, v133
	s_and_saveexec_b64 s[52:53], s[40:41]
	s_cbranch_execz .LBB0_911
	s_waitcnt lgkmcnt(0)
	v_add_f32_e32 v132, v132, v133
	ds_write_b32 v180, v132 offset:2048
.LBB0_911:
	s_or_b64 exec, exec, s[52:53]
	v_max_f32_e32 v131, v131, v131
	v_max_f32_e32 v130, v130, v130
	v_max_f32_e32 v130, v130, v131
	v_max3_f32 v129, v128, v129, v130
	v_mov_b32_e32 v128, v35
	v_pk_mul_f32 v[128:129], v[128:129], s[34:35] op_sel_hi:[1,0]
	s_nop 0
	v_fma_f32 v35, v44, s34, -v129
	v_exp_f32_e32 v44, v35
	v_fma_f32 v35, v45, s34, -v129
	v_exp_f32_e32 v45, v35
	v_fma_f32 v35, v46, s34, -v129
	v_exp_f32_e32 v46, v35
	v_fma_f32 v35, v47, s34, -v129
	v_exp_f32_e32 v47, v35
	v_fma_f32 v40, v40, s34, -v129
	v_add_f32_e32 v35, 0, v44
	v_exp_f32_e32 v40, v40
	v_fma_f32 v41, v41, s34, -v129
	v_add_f32_e32 v35, v45, v35
	v_exp_f32_e32 v41, v41
	v_fma_f32 v42, v42, s34, -v129
	v_add_f32_e32 v35, v46, v35
	v_exp_f32_e32 v42, v42
	v_fma_f32 v43, v43, s34, -v129
	v_add_f32_e32 v35, v47, v35
	v_exp_f32_e32 v43, v43
	v_fma_f32 v36, v36, s34, -v129
	v_add_f32_e32 v35, v40, v35
	v_exp_f32_e32 v36, v36
	v_fma_f32 v37, v37, s34, -v129
	v_add_f32_e32 v35, v41, v35
	v_exp_f32_e32 v37, v37
	v_fma_f32 v38, v38, s34, -v129
	v_add_f32_e32 v35, v42, v35
	v_exp_f32_e32 v38, v38
	v_fma_f32 v39, v39, s34, -v129
	v_add_f32_e32 v35, v43, v35
	v_exp_f32_e32 v39, v39
	v_add_f32_e32 v35, v36, v35
	v_fma_f32 v32, v32, s34, -v129
	v_add_f32_e32 v35, v37, v35
	v_exp_f32_e32 v32, v32
	v_fma_f32 v33, v33, s34, -v129
	v_add_f32_e32 v35, v38, v35
	v_exp_f32_e32 v33, v33
	v_fma_f32 v34, v34, s34, -v129
	v_add_f32_e32 v130, v39, v35
	v_exp_f32_e32 v34, v34
	v_sub_f32_e32 v35, v128, v129
	v_exp_f32_e32 v35, v35
	v_add_f32_e32 v128, v32, v130
	v_add_f32_e32 v128, v33, v128
	v_add_f32_e32 v128, v34, v128
	v_add_f32_e32 v128, v35, v128
	v_mov_b32_e32 v129, v128
	v_mov_b32_e32 v240, v128
	s_nop 1
	v_permlane16_swap_b32_e32 v240, v129
	s_waitcnt lgkmcnt(0)
	v_add_f32_e32 v128, v240, v129
	v_mov_b32_e32 v129, v128
	v_mov_b32_e32 v240, v128
	s_nop 1
	v_permlane32_swap_b32_e32 v240, v129
	s_and_saveexec_b64 s[52:53], s[40:41]
	s_cbranch_execz .LBB0_913
	s_waitcnt lgkmcnt(0)
	v_add_f32_e32 v128, v128, v129
	ds_write_b32 v180, v128 offset:2304
; template <bool ISMAX> DI void tile_row_reduce(float (&p)[2][4], LAS float* red, int wr, int wc, int fr, int fq) {
;     ...
;         for (int m = 0; m < 4; ++m) { float v = p[ai][m]; const float a = __shfl_xor(v, 16); v = ISMAX ? fmaxf(v, a) : v + a; const float b = __shfl_xor(v, 32); v = ISMAX ? fmaxf(v, b) : v + b;
;             if (fq == 0) red[(ai * 128 + wr * 64 + m * 16 + fr) * 4 + wc] = v; }
;     DI void operator()(Acc& acc, const Unit& u, int wr, int wc, int fr, int fq, LAS unsigned char* lds) const {
;     ...
;         for (int ai = 0; ai < 2; ++ai)
; #pragma unroll
;             for (int m = 0; m < 4; ++m) { const float mx = part[ai][m] * LOG2E; float s = 0.f;
; #pragma unroll
;                 for (int bj = 0; bj < 2; ++bj)
; #pragma unroll
;                     for (int n = 0; n < 2; ++n) { f32x4 v = acc[ai][bj][m][n];
; #pragma unroll
;                         for (int e = 0; e < 4; ++e) { v[e] = __builtin_amdgcn_exp2f(v[e] * LOG2E - mx); s += v[e]; }
;                         acc[ai][bj][m][n] = v; }
;                 part2[ai][m] = s; }
;         tile_row_reduce<false>(part2, red + 1024, wr, wc, fr, fq);
.LBB0_913:
	s_or_b64 exec, exec, s[52:53]
	v_max_f32_e32 v119, v119, v119
	v_max_f32_e32 v118, v118, v118
	v_max_f32_e32 v118, v118, v119
	v_max3_f32 v117, v116, v117, v118
	v_mov_b32_e32 v116, v19
	v_pk_mul_f32 v[116:117], v[116:117], s[34:35] op_sel_hi:[1,0]
	s_nop 0
	v_fma_f32 v19, v28, s34, -v117
	v_exp_f32_e32 v28, v19
	v_fma_f32 v19, v29, s34, -v117
	v_exp_f32_e32 v29, v19
	v_fma_f32 v19, v30, s34, -v117
	v_exp_f32_e32 v30, v19
	v_fma_f32 v19, v31, s34, -v117
	v_exp_f32_e32 v31, v19
	v_fma_f32 v24, v24, s34, -v117
	v_add_f32_e32 v19, 0, v28
	v_exp_f32_e32 v24, v24
	v_fma_f32 v25, v25, s34, -v117
	v_add_f32_e32 v19, v29, v19
	v_exp_f32_e32 v25, v25
	v_fma_f32 v26, v26, s34, -v117
	v_add_f32_e32 v19, v30, v19
	v_exp_f32_e32 v26, v26
	v_fma_f32 v27, v27, s34, -v117
	v_add_f32_e32 v19, v31, v19
	v_exp_f32_e32 v27, v27
	v_fma_f32 v20, v20, s34, -v117
	v_add_f32_e32 v19, v24, v19
	v_exp_f32_e32 v20, v20
	v_fma_f32 v21, v21, s34, -v117
	v_add_f32_e32 v19, v25, v19
	v_exp_f32_e32 v21, v21
	v_fma_f32 v22, v22, s34, -v117
	v_add_f32_e32 v19, v26, v19
	v_exp_f32_e32 v22, v22
	v_fma_f32 v23, v23, s34, -v117
	v_add_f32_e32 v19, v27, v19
	v_exp_f32_e32 v23, v23
	v_add_f32_e32 v19, v20, v19
	v_fma_f32 v16, v16, s34, -v117
	v_add_f32_e32 v19, v21, v19
	v_exp_f32_e32 v16, v16
	v_fma_f32 v17, v17, s34, -v117
	v_add_f32_e32 v19, v22, v19
	v_exp_f32_e32 v17, v17
	v_fma_f32 v18, v18, s34, -v117
	v_add_f32_e32 v118, v23, v19
	v_exp_f32_e32 v18, v18
	v_sub_f32_e32 v19, v116, v117
	v_exp_f32_e32 v19, v19
	v_add_f32_e32 v116, v16, v118
	v_add_f32_e32 v116, v17, v116
	v_add_f32_e32 v116, v18, v116
	v_add_f32_e32 v116, v19, v116
	v_mov_b32_e32 v117, v116
	v_mov_b32_e32 v240, v116
	s_nop 1
	v_permlane16_swap_b32_e32 v240, v117
	s_waitcnt lgkmcnt(0)
	v_add_f32_e32 v116, v240, v117
	v_mov_b32_e32 v117, v116
	v_mov_b32_e32 v240, v116
	s_nop 1
	v_permlane32_swap_b32_e32 v240, v117
	s_and_saveexec_b64 s[52:53], s[40:41]
	s_cbranch_execz .LBB0_915
	s_waitcnt lgkmcnt(0)
	v_add_f32_e32 v116, v116, v117
	ds_write_b32 v180, v116 offset:2560
.LBB0_915:
	s_or_b64 exec, exec, s[52:53]
	v_max_f32_e32 v115, v115, v115
	v_max_f32_e32 v114, v114, v114
	v_max_f32_e32 v114, v114, v115
	v_max3_f32 v113, v112, v113, v114
	v_mov_b32_e32 v112, v3
	v_pk_mul_f32 v[112:113], v[112:113], s[34:35] op_sel_hi:[1,0]
	s_nop 0
	v_fma_f32 v3, v12, s34, -v113
	v_exp_f32_e32 v12, v3
	v_fma_f32 v3, v13, s34, -v113
	v_exp_f32_e32 v13, v3
	v_fma_f32 v3, v14, s34, -v113
	v_exp_f32_e32 v14, v3
	v_fma_f32 v3, v15, s34, -v113
	v_exp_f32_e32 v15, v3
	v_fma_f32 v8, v8, s34, -v113
	v_add_f32_e32 v3, 0, v12
	v_exp_f32_e32 v8, v8
	v_fma_f32 v9, v9, s34, -v113
	v_add_f32_e32 v3, v13, v3
	v_exp_f32_e32 v9, v9
	v_fma_f32 v10, v10, s34, -v113
	v_add_f32_e32 v3, v14, v3
	v_exp_f32_e32 v10, v10
	v_fma_f32 v11, v11, s34, -v113
	v_add_f32_e32 v3, v15, v3
	v_exp_f32_e32 v11, v11
	v_fma_f32 v4, v4, s34, -v113
	v_add_f32_e32 v3, v8, v3
	v_exp_f32_e32 v4, v4
	v_fma_f32 v5, v5, s34, -v113
	v_add_f32_e32 v3, v9, v3
	v_exp_f32_e32 v5, v5
	v_fma_f32 v6, v6, s34, -v113
	v_add_f32_e32 v3, v10, v3
	v_exp_f32_e32 v6, v6
	v_fma_f32 v7, v7, s34, -v113
	v_add_f32_e32 v3, v11, v3
	v_exp_f32_e32 v7, v7
	v_add_f32_e32 v3, v4, v3
	v_fma_f32 v0, v0, s34, -v113
	v_add_f32_e32 v3, v5, v3
	v_exp_f32_e32 v0, v0
	v_fma_f32 v1, v1, s34, -v113
	v_add_f32_e32 v3, v6, v3
	v_exp_f32_e32 v1, v1
	v_fma_f32 v2, v2, s34, -v113
	v_add_f32_e32 v114, v7, v3
	v_exp_f32_e32 v2, v2
	v_sub_f32_e32 v3, v112, v113
	v_exp_f32_e32 v3, v3
	v_add_f32_e32 v112, v0, v114
	v_add_f32_e32 v112, v1, v112
	v_add_f32_e32 v112, v2, v112
	v_add_f32_e32 v112, v3, v112
	v_mov_b32_e32 v113, v112
	v_mov_b32_e32 v240, v112
	s_nop 1
	v_permlane16_swap_b32_e32 v240, v113
	s_waitcnt lgkmcnt(0)
	v_add_f32_e32 v112, v240, v113
	v_mov_b32_e32 v113, v112
	v_mov_b32_e32 v240, v112
	s_nop 1
	v_permlane32_swap_b32_e32 v240, v113
	s_and_saveexec_b64 s[52:53], s[40:41]
	s_cbranch_execz .LBB0_917
	s_waitcnt lgkmcnt(0)
	v_add_f32_e32 v112, v112, v113
	ds_write_b32 v180, v112 offset:2816

; DI unsigned pk2(float lo, float hi) { f32x2 v = {lo, hi}; bf16x2_t b = __builtin_convertvector(v, bf16x2_t); return __builtin_bit_cast(unsigned, b); }
; DI float bflo(unsigned w) { return __uint_as_float(w << 16); }
; DI float bfhi(unsigned w) { return __uint_as_float(w & 0xffff0000u); }
;     DI void operator()(Acc& acc, const Unit& u, int wr, int wc, int fr, int fq, LAS unsigned char* lds) const {
;     ...
;             for (int m = 0; m < 4; ++m) { const int row = u.pm * BM + ai * HALF + wr * 64 + m * 16 + fr; const size_t off = (size_t)row * DM + col0; float ss = 0.f;
; #pragma unroll
;                 for (int bj = 0; bj < 2; ++bj) { const size_t o = off + bj * HALF;
;                     f32x4 b0, b1;
;                     if (BASE_BF16) { const u32x4 w = *(const u32x4*)((const bf16_t*)base + o); b0 = (f32x4){bflo(w.x), bfhi(w.x), bflo(w.y), bfhi(w.y)}; b1 = (f32x4){bflo(w.z), bfhi(w.z), bflo(w.w), bfhi(w.w)}; }
;                     else { b0 = *(const f32x4*)((const float*)base + o); b1 = *(const f32x4*)((const float*)base + o + 4); }
;                     const f32x4 v0 = b0 + acc[ai][bj][m][0], v1 = b1 + acc[ai][bj][m][1];
;                     if (OUT_F32) { __builtin_nontemporal_store(v0, (f32x4*)(out + o)); __builtin_nontemporal_store(v1, (f32x4*)(out + o + 4)); }
;                     if (OUT_BF16) { u32x4 w; w.x = pk2(v0.x, v0.y); w.y = pk2(v0.z, v0.w); w.z = pk2(v1.x, v1.y); w.w = pk2(v1.z, v1.w); *(u32x4*)(hb + o) = w;
;                         ss += ((v0.x * v0.x + v0.y * v0.y) + (v0.z * v0.z + v0.w * v0.w)) + ((v1.x * v1.x + v1.y * v1.y) + (v1.z * v1.z + v1.w * v1.w)); } }
;                 part[ai][m] = ss; }
.LBB0_992:
	v_lshl_add_u32 v144, s22, 8, v148
	v_lshl_or_b32 v146, s14, 8, v150
	v_ashrrev_i32_e32 v145, 31, v144
	v_ashrrev_i32_e32 v147, 31, v146
	v_lshlrev_b64 v[156:157], 11, v[144:145]
	v_lshl_add_u64 v[156:157], s[26:27], 0, v[156:157]
	v_lshlrev_b64 v[146:147], 1, v[146:147]
	v_lshl_add_u64 v[160:161], v[156:157], 0, v[146:147]
	global_load_dwordx4 v[156:159], v[160:161], off
	s_waitcnt vmcnt(0)
	v_lshlrev_b32_e32 v166, 16, v156
	v_and_b32_e32 v167, 0xffff0000, v156
	v_lshlrev_b32_e32 v156, 16, v157
	v_and_b32_e32 v157, 0xffff0000, v157
	v_lshlrev_b32_e32 v168, 16, v158
	v_and_b32_e32 v169, 0xffff0000, v158
	v_lshlrev_b32_e32 v158, 16, v159
	v_and_b32_e32 v159, 0xffff0000, v159
	v_pk_add_f32 v[126:127], v[126:127], v[156:157]
	v_pk_add_f32 v[124:125], v[124:125], v[166:167]
	v_pk_add_f32 v[156:157], v[122:123], v[158:159]
	v_pk_add_f32 v[158:159], v[120:121], v[168:169]
	v_cvt_pk_bf16_f32 v120, v124, v125
	v_cvt_pk_bf16_f32 v121, v126, v127
	v_cvt_pk_bf16_f32 v122, v158, v159
	v_cvt_pk_bf16_f32 v123, v156, v157
	global_store_dwordx4 v[160:161], v[120:123], off
	s_nop 1
	v_mul_f32_e32 v120, v125, v125
	v_mul_f32_e32 v121, v127, v127
	v_fmac_f32_e32 v120, v124, v124
	v_fmac_f32_e32 v121, v126, v126
	v_add_f32_e32 v120, v120, v121
	v_mul_f32_e32 v121, v159, v159
	v_mul_f32_e32 v122, v157, v157
	v_fmac_f32_e32 v121, v158, v158
	v_fmac_f32_e32 v122, v156, v156
	v_add_f32_e32 v121, v121, v122
	v_add_f32_e32 v155, v120, v121
	global_load_dwordx4 v[120:123], v[160:161], off offset:256
	s_waitcnt vmcnt(0)
	v_lshlrev_b32_e32 v124, 16, v120
	v_and_b32_e32 v125, 0xffff0000, v120
	v_lshlrev_b32_e32 v120, 16, v121
	v_and_b32_e32 v121, 0xffff0000, v121
	v_lshlrev_b32_e32 v126, 16, v122
	v_and_b32_e32 v127, 0xffff0000, v122
	v_lshlrev_b32_e32 v122, 16, v123
	v_and_b32_e32 v123, 0xffff0000, v123
	v_pk_add_f32 v[118:119], v[118:119], v[120:121]
	v_pk_add_f32 v[116:117], v[116:117], v[124:125]
	v_pk_add_f32 v[120:121], v[114:115], v[122:123]
	v_pk_add_f32 v[122:123], v[112:113], v[126:127]
	v_cvt_pk_bf16_f32 v112, v116, v117
	v_cvt_pk_bf16_f32 v113, v118, v119
	v_cvt_pk_bf16_f32 v114, v122, v123
	v_cvt_pk_bf16_f32 v115, v120, v121
	global_store_dwordx4 v[160:161], v[112:115], off offset:256
	s_nop 1
	v_mul_f32_e32 v112, v117, v117
	v_mul_f32_e32 v113, v119, v119
	v_fmac_f32_e32 v112, v116, v116
	v_fmac_f32_e32 v113, v118, v118
	v_add_f32_e32 v112, v112, v113
	v_mul_f32_e32 v113, v123, v123
	v_mul_f32_e32 v114, v121, v121
	v_fmac_f32_e32 v113, v122, v122
	v_fmac_f32_e32 v114, v120, v120
	v_add_f32_e32 v113, v113, v114
	v_add_f32_e32 v112, v112, v113
	v_add_f32_e32 v155, v155, v112
	v_or_b32_e32 v112, 16, v144
	v_ashrrev_i32_e32 v113, 31, v112
	v_lshlrev_b64 v[114:115], 11, v[112:113]
	v_lshl_add_u64 v[114:115], s[26:27], 0, v[114:115]
	v_lshl_add_u64 v[120:121], v[114:115], 0, v[146:147]
	global_load_dwordx4 v[114:117], v[120:121], off
	s_waitcnt vmcnt(0)
	v_lshlrev_b32_e32 v118, 16, v114
	v_and_b32_e32 v119, 0xffff0000, v114
	v_lshlrev_b32_e32 v114, 16, v115
	v_and_b32_e32 v115, 0xffff0000, v115
	v_lshlrev_b32_e32 v122, 16, v116
	v_and_b32_e32 v123, 0xffff0000, v116
	v_lshlrev_b32_e32 v116, 16, v117
	v_and_b32_e32 v117, 0xffff0000, v117
	v_pk_add_f32 v[110:111], v[110:111], v[114:115]
	v_pk_add_f32 v[108:109], v[108:109], v[118:119]
	v_pk_add_f32 v[106:107], v[106:107], v[116:117]
	v_pk_add_f32 v[104:105], v[104:105], v[122:123]
	v_cvt_pk_bf16_f32 v114, v108, v109
	v_cvt_pk_bf16_f32 v115, v110, v111
	v_cvt_pk_bf16_f32 v116, v104, v105
	v_cvt_pk_bf16_f32 v117, v106, v107
	global_store_dwordx4 v[120:121], v[114:117], off
	global_load_dwordx4 v[114:117], v[120:121], off offset:256
	s_waitcnt vmcnt(0)
	v_lshlrev_b32_e32 v118, 16, v114
	v_and_b32_e32 v119, 0xffff0000, v114
	v_lshlrev_b32_e32 v114, 16, v115
	v_and_b32_e32 v115, 0xffff0000, v115
	v_lshlrev_b32_e32 v122, 16, v116
	v_and_b32_e32 v123, 0xffff0000, v116
	v_lshlrev_b32_e32 v116, 16, v117
	v_and_b32_e32 v117, 0xffff0000, v117
	v_pk_add_f32 v[102:103], v[102:103], v[114:115]
	v_pk_add_f32 v[114:115], v[100:101], v[118:119]
	v_pk_add_f32 v[98:99], v[98:99], v[116:117]
	v_pk_add_f32 v[100:101], v[96:97], v[122:123]
	v_or_b32_e32 v96, 32, v144
	v_cvt_pk_bf16_f32 v116, v114, v115
	v_cvt_pk_bf16_f32 v117, v102, v103
	v_cvt_pk_bf16_f32 v118, v100, v101
	v_cvt_pk_bf16_f32 v119, v98, v99
	v_ashrrev_i32_e32 v97, 31, v96
	global_store_dwordx4 v[120:121], v[116:119], off offset:256
	s_nop 1
	v_lshlrev_b64 v[116:117], 11, v[96:97]
	v_lshl_add_u64 v[116:117], s[26:27], 0, v[116:117]
	v_lshl_add_u64 v[122:123], v[116:117], 0, v[146:147]
	global_load_dwordx4 v[116:119], v[122:123], off
	s_waitcnt vmcnt(0)
	v_lshlrev_b32_e32 v120, 16, v116
	v_and_b32_e32 v121, 0xffff0000, v116
	v_lshlrev_b32_e32 v116, 16, v117
	v_and_b32_e32 v117, 0xffff0000, v117
	v_lshlrev_b32_e32 v124, 16, v118
	v_and_b32_e32 v125, 0xffff0000, v118
	v_lshlrev_b32_e32 v118, 16, v119
	v_and_b32_e32 v119, 0xffff0000, v119
	v_pk_add_f32 v[94:95], v[94:95], v[116:117]
	v_pk_add_f32 v[92:93], v[92:93], v[120:121]
	v_pk_add_f32 v[90:91], v[90:91], v[118:119]
	v_pk_add_f32 v[88:89], v[88:89], v[124:125]
	v_cvt_pk_bf16_f32 v116, v92, v93
	v_cvt_pk_bf16_f32 v117, v94, v95
	v_cvt_pk_bf16_f32 v118, v88, v89
	v_cvt_pk_bf16_f32 v119, v90, v91
	global_store_dwordx4 v[122:123], v[116:119], off
	global_load_dwordx4 v[116:119], v[122:123], off offset:256
	s_waitcnt vmcnt(0)
; DI unsigned pk2(float lo, float hi) { f32x2 v = {lo, hi}; bf16x2_t b = __builtin_convertvector(v, bf16x2_t); return __builtin_bit_cast(unsigned, b); }
; DI float bflo(unsigned w) { return __uint_as_float(w << 16); }
; DI float bfhi(unsigned w) { return __uint_as_float(w & 0xffff0000u); }
;     DI void operator()(Acc& acc, const Unit& u, int wr, int wc, int fr, int fq, LAS unsigned char* lds) const {
;     ...
;             for (int m = 0; m < 4; ++m) { const int row = u.pm * BM + ai * HALF + wr * 64 + m * 16 + fr; const size_t off = (size_t)row * DM + col0; float ss = 0.f;
; #pragma unroll
;                 for (int bj = 0; bj < 2; ++bj) { const size_t o = off + bj * HALF;
;                     f32x4 b0, b1;
;                     if (BASE_BF16) { const u32x4 w = *(const u32x4*)((const bf16_t*)base + o); b0 = (f32x4){bflo(w.x), bfhi(w.x), bflo(w.y), bfhi(w.y)}; b1 = (f32x4){bflo(w.z), bfhi(w.z), bflo(w.w), bfhi(w.w)}; }
;                     else { b0 = *(const f32x4*)((const float*)base + o); b1 = *(const f32x4*)((const float*)base + o + 4); }
;                     const f32x4 v0 = b0 + acc[ai][bj][m][0], v1 = b1 + acc[ai][bj][m][1];
;                     if (OUT_F32) { __builtin_nontemporal_store(v0, (f32x4*)(out + o)); __builtin_nontemporal_store(v1, (f32x4*)(out + o + 4)); }
;                     if (OUT_BF16) { u32x4 w; w.x = pk2(v0.x, v0.y); w.y = pk2(v0.z, v0.w); w.z = pk2(v1.x, v1.y); w.w = pk2(v1.z, v1.w); *(u32x4*)(hb + o) = w;
	v_lshlrev_b32_e32 v120, 16, v116
	v_and_b32_e32 v121, 0xffff0000, v116
	v_lshlrev_b32_e32 v116, 16, v117
	v_and_b32_e32 v117, 0xffff0000, v117
	v_lshlrev_b32_e32 v124, 16, v118
	v_and_b32_e32 v125, 0xffff0000, v118
	v_lshlrev_b32_e32 v118, 16, v119
	v_and_b32_e32 v119, 0xffff0000, v119
	v_pk_add_f32 v[86:87], v[86:87], v[116:117]
	v_pk_add_f32 v[116:117], v[84:85], v[120:121]
	v_pk_add_f32 v[82:83], v[82:83], v[118:119]
	v_pk_add_f32 v[84:85], v[80:81], v[124:125]
	v_or_b32_e32 v80, 48, v144
	v_cvt_pk_bf16_f32 v118, v116, v117
	v_cvt_pk_bf16_f32 v119, v86, v87
	v_cvt_pk_bf16_f32 v120, v84, v85
	v_cvt_pk_bf16_f32 v121, v82, v83
	v_ashrrev_i32_e32 v81, 31, v80
	global_store_dwordx4 v[122:123], v[118:121], off offset:256
	s_nop 1
	v_lshlrev_b64 v[118:119], 11, v[80:81]
	v_lshl_add_u64 v[118:119], s[26:27], 0, v[118:119]
	v_lshl_add_u64 v[120:121], v[118:119], 0, v[146:147]
	global_load_dwordx4 v[122:125], v[120:121], off
	s_waitcnt vmcnt(0)
	v_lshlrev_b32_e32 v118, 16, v122
	v_and_b32_e32 v119, 0xffff0000, v122
	v_lshlrev_b32_e32 v122, 16, v123
	v_and_b32_e32 v123, 0xffff0000, v123
	v_lshlrev_b32_e32 v126, 16, v124
	v_and_b32_e32 v127, 0xffff0000, v124
	v_lshlrev_b32_e32 v124, 16, v125
	v_and_b32_e32 v125, 0xffff0000, v125
	v_pk_add_f32 v[78:79], v[78:79], v[122:123]
	v_pk_add_f32 v[76:77], v[76:77], v[118:119]
	v_pk_add_f32 v[74:75], v[74:75], v[124:125]
	v_pk_add_f32 v[72:73], v[72:73], v[126:127]
	v_cvt_pk_bf16_f32 v122, v76, v77
	v_cvt_pk_bf16_f32 v123, v78, v79
	v_cvt_pk_bf16_f32 v124, v72, v73
	v_cvt_pk_bf16_f32 v125, v74, v75
	global_store_dwordx4 v[120:121], v[122:125], off
	global_load_dwordx4 v[122:125], v[120:121], off offset:256
	s_waitcnt vmcnt(0)
	v_lshlrev_b32_e32 v118, 16, v122
	v_and_b32_e32 v119, 0xffff0000, v122
	v_lshlrev_b32_e32 v122, 16, v123
	v_and_b32_e32 v123, 0xffff0000, v123
	v_lshlrev_b32_e32 v126, 16, v124
	v_and_b32_e32 v127, 0xffff0000, v124
	v_lshlrev_b32_e32 v124, 16, v125
	v_and_b32_e32 v125, 0xffff0000, v125
	v_pk_add_f32 v[70:71], v[70:71], v[122:123]
	v_pk_add_f32 v[118:119], v[68:69], v[118:119]
	v_pk_add_f32 v[66:67], v[66:67], v[124:125]
	v_pk_add_f32 v[68:69], v[64:65], v[126:127]
	v_add_u32_e32 v64, 0x80, v144
	v_cvt_pk_bf16_f32 v122, v118, v119
	v_cvt_pk_bf16_f32 v123, v70, v71
	v_cvt_pk_bf16_f32 v124, v68, v69
	v_cvt_pk_bf16_f32 v125, v66, v67
	v_ashrrev_i32_e32 v65, 31, v64
	global_store_dwordx4 v[120:121], v[122:125], off offset:256
	v_lshlrev_b64 v[120:121], 11, v[64:65]
	v_lshl_add_u64 v[120:121], s[26:27], 0, v[120:121]
	v_lshl_add_u64 v[126:127], v[120:121], 0, v[146:147]
	global_load_dwordx4 v[120:123], v[126:127], off
	s_waitcnt vmcnt(0)
	v_lshlrev_b32_e32 v124, 16, v120
	v_and_b32_e32 v125, 0xffff0000, v120
	v_lshlrev_b32_e32 v120, 16, v121
	v_and_b32_e32 v121, 0xffff0000, v121
	v_lshlrev_b32_e32 v156, 16, v122
	v_and_b32_e32 v157, 0xffff0000, v122
	v_lshlrev_b32_e32 v122, 16, v123
	v_and_b32_e32 v123, 0xffff0000, v123
	v_pk_add_f32 v[62:63], v[62:63], v[120:121]
	v_pk_add_f32 v[60:61], v[60:61], v[124:125]
	v_pk_add_f32 v[58:59], v[58:59], v[122:123]
	v_pk_add_f32 v[56:57], v[56:57], v[156:157]
	v_cvt_pk_bf16_f32 v120, v60, v61
	v_cvt_pk_bf16_f32 v121, v62, v63
	v_cvt_pk_bf16_f32 v122, v56, v57
	v_cvt_pk_bf16_f32 v123, v58, v59
	global_store_dwordx4 v[126:127], v[120:123], off
	global_load_dwordx4 v[120:123], v[126:127], off offset:256
	s_waitcnt vmcnt(0)
	v_lshlrev_b32_e32 v124, 16, v120
	v_and_b32_e32 v125, 0xffff0000, v120
	v_lshlrev_b32_e32 v120, 16, v121
	v_and_b32_e32 v121, 0xffff0000, v121
	v_lshlrev_b32_e32 v156, 16, v122
	v_and_b32_e32 v157, 0xffff0000, v122
	v_lshlrev_b32_e32 v122, 16, v123
	v_and_b32_e32 v123, 0xffff0000, v123
	v_pk_add_f32 v[54:55], v[54:55], v[120:121]
	v_pk_add_f32 v[120:121], v[52:53], v[124:125]
	v_pk_add_f32 v[50:51], v[50:51], v[122:123]
	v_pk_add_f32 v[52:53], v[48:49], v[156:157]
	v_add_u32_e32 v48, 0x90, v144
	v_cvt_pk_bf16_f32 v122, v120, v121
	v_cvt_pk_bf16_f32 v123, v54, v55
	v_cvt_pk_bf16_f32 v124, v52, v53
	v_cvt_pk_bf16_f32 v125, v50, v51
	v_ashrrev_i32_e32 v49, 31, v48
	global_store_dwordx4 v[126:127], v[122:125], off offset:256
	s_nop 1
	v_lshlrev_b64 v[122:123], 11, v[48:49]
	v_lshl_add_u64 v[122:123], s[26:27], 0, v[122:123]
	v_lshl_add_u64 v[156:157], v[122:123], 0, v[146:147]
	global_load_dwordx4 v[122:125], v[156:157], off
	s_waitcnt vmcnt(0)
	v_lshlrev_b32_e32 v126, 16, v122
	v_and_b32_e32 v127, 0xffff0000, v122
	v_lshlrev_b32_e32 v122, 16, v123
	v_and_b32_e32 v123, 0xffff0000, v123
	v_lshlrev_b32_e32 v158, 16, v124
	v_and_b32_e32 v159, 0xffff0000, v124
	v_lshlrev_b32_e32 v124, 16, v125
	v_and_b32_e32 v125, 0xffff0000, v125
	v_pk_add_f32 v[46:47], v[46:47], v[122:123]
	v_pk_add_f32 v[44:45], v[44:45], v[126:127]
	v_pk_add_f32 v[42:43], v[42:43], v[124:125]
	v_pk_add_f32 v[40:41], v[40:41], v[158:159]
	v_cvt_pk_bf16_f32 v122, v44, v45
	v_cvt_pk_bf16_f32 v123, v46, v47
	v_cvt_pk_bf16_f32 v124, v40, v41
	v_cvt_pk_bf16_f32 v125, v42, v43
	global_store_dwordx4 v[156:157], v[122:125], off
	global_load_dwordx4 v[122:125], v[156:157], off offset:256
	s_waitcnt vmcnt(0)
	v_lshlrev_b32_e32 v126, 16, v122
	v_and_b32_e32 v127, 0xffff0000, v122
	v_lshlrev_b32_e32 v122, 16, v123
	v_and_b32_e32 v123, 0xffff0000, v123
	v_lshlrev_b32_e32 v158, 16, v124
	v_and_b32_e32 v159, 0xffff0000, v124
	v_lshlrev_b32_e32 v124, 16, v125
	v_and_b32_e32 v125, 0xffff0000, v125
	v_pk_add_f32 v[38:39], v[38:39], v[122:123]
	v_pk_add_f32 v[122:123], v[36:37], v[126:127]
	v_pk_add_f32 v[34:35], v[34:35], v[124:125]
	v_pk_add_f32 v[36:37], v[32:33], v[158:159]
	v_add_u32_e32 v32, 0xa0, v144
	v_cvt_pk_bf16_f32 v124, v122, v123
	v_cvt_pk_bf16_f32 v125, v38, v39
	v_cvt_pk_bf16_f32 v126, v36, v37
	v_cvt_pk_bf16_f32 v127, v34, v35
	v_ashrrev_i32_e32 v33, 31, v32
	global_store_dwordx4 v[156:157], v[124:127], off offset:256
	s_nop 1
	v_lshlrev_b64 v[124:125], 11, v[32:33]
	v_lshl_add_u64 v[124:125], s[26:27], 0, v[124:125]
	v_lshl_add_u64 v[160:161], v[124:125], 0, v[146:147]
	global_load_dwordx4 v[124:127], v[160:161], off
	s_waitcnt vmcnt(0)
; DI unsigned pk2(float lo, float hi) { f32x2 v = {lo, hi}; bf16x2_t b = __builtin_convertvector(v, bf16x2_t); return __builtin_bit_cast(unsigned, b); }
; DI float bflo(unsigned w) { return __uint_as_float(w << 16); }
; DI float bfhi(unsigned w) { return __uint_as_float(w & 0xffff0000u); }
; template <bool ISMAX> DI void tile_row_reduce(float (&p)[2][4], LAS float* red, int wr, int wc, int fr, int fq) {
;     ...
;     for (int ai = 0; ai < 2; ++ai)
; #pragma unroll
;         for (int m = 0; m < 4; ++m) { float v = p[ai][m]; const float a = __shfl_xor(v, 16); v = ISMAX ? fmaxf(v, a) : v + a; const float b = __shfl_xor(v, 32); v = ISMAX ? fmaxf(v, b) : v + b;
;             if (fq == 0) red[(ai * 128 + wr * 64 + m * 16 + fr) * 4 + wc] = v; }
;     DI void operator()(Acc& acc, const Unit& u, int wr, int wc, int fr, int fq, LAS unsigned char* lds) const {
;     ...
;                     if (BASE_BF16) { const u32x4 w = *(const u32x4*)((const bf16_t*)base + o); b0 = (f32x4){bflo(w.x), bfhi(w.x), bflo(w.y), bfhi(w.y)}; b1 = (f32x4){bflo(w.z), bfhi(w.z), bflo(w.w), bfhi(w.w)}; }
;                     else { b0 = *(const f32x4*)((const float*)base + o); b1 = *(const f32x4*)((const float*)base + o + 4); }
;                     const f32x4 v0 = b0 + acc[ai][bj][m][0], v1 = b1 + acc[ai][bj][m][1];
;                     if (OUT_F32) { __builtin_nontemporal_store(v0, (f32x4*)(out + o)); __builtin_nontemporal_store(v1, (f32x4*)(out + o + 4)); }
;                     if (OUT_BF16) { u32x4 w; w.x = pk2(v0.x, v0.y); w.y = pk2(v0.z, v0.w); w.z = pk2(v1.x, v1.y); w.w = pk2(v1.z, v1.w); *(u32x4*)(hb + o) = w;
;                         ss += ((v0.x * v0.x + v0.y * v0.y) + (v0.z * v0.z + v0.w * v0.w)) + ((v1.x * v1.x + v1.y * v1.y) + (v1.z * v1.z + v1.w * v1.w)); } }
;                 part[ai][m] = ss; }
	v_lshlrev_b32_e32 v156, 16, v124
	v_and_b32_e32 v157, 0xffff0000, v124
	v_lshlrev_b32_e32 v124, 16, v125
	v_and_b32_e32 v125, 0xffff0000, v125
	v_lshlrev_b32_e32 v158, 16, v126
	v_and_b32_e32 v159, 0xffff0000, v126
	v_lshlrev_b32_e32 v126, 16, v127
	v_and_b32_e32 v127, 0xffff0000, v127
	v_pk_add_f32 v[30:31], v[30:31], v[124:125]
	v_pk_add_f32 v[28:29], v[28:29], v[156:157]
	v_pk_add_f32 v[26:27], v[26:27], v[126:127]
	v_pk_add_f32 v[24:25], v[24:25], v[158:159]
	v_cvt_pk_bf16_f32 v124, v28, v29
	v_cvt_pk_bf16_f32 v125, v30, v31
	v_cvt_pk_bf16_f32 v126, v24, v25
	v_cvt_pk_bf16_f32 v127, v26, v27
	global_store_dwordx4 v[160:161], v[124:127], off
	global_load_dwordx4 v[124:127], v[160:161], off offset:256
	s_waitcnt vmcnt(0)
	v_lshlrev_b32_e32 v156, 16, v124
	v_and_b32_e32 v157, 0xffff0000, v124
	v_lshlrev_b32_e32 v124, 16, v125
	v_and_b32_e32 v125, 0xffff0000, v125
	v_lshlrev_b32_e32 v158, 16, v126
	v_and_b32_e32 v159, 0xffff0000, v126
	v_pk_add_f32 v[22:23], v[22:23], v[124:125]
	v_pk_add_f32 v[124:125], v[20:21], v[156:157]
	v_pk_add_f32 v[20:21], v[16:17], v[158:159]
	v_add_u32_e32 v16, 0xb0, v144
	v_lshlrev_b32_e32 v126, 16, v127
	v_and_b32_e32 v127, 0xffff0000, v127
	v_ashrrev_i32_e32 v17, 31, v16
	v_pk_add_f32 v[18:19], v[18:19], v[126:127]
	v_lshlrev_b64 v[126:127], 11, v[16:17]
	v_lshl_add_u64 v[126:127], s[26:27], 0, v[126:127]
	v_cvt_pk_bf16_f32 v156, v124, v125
	v_cvt_pk_bf16_f32 v157, v22, v23
	v_cvt_pk_bf16_f32 v158, v20, v21
	v_cvt_pk_bf16_f32 v159, v18, v19
	v_lshl_add_u64 v[126:127], v[126:127], 0, v[146:147]
	global_store_dwordx4 v[160:161], v[156:159], off offset:256
	global_load_dwordx4 v[156:159], v[126:127], off
	s_waitcnt vmcnt(0)
	v_lshlrev_b32_e32 v146, 16, v156
	v_and_b32_e32 v147, 0xffff0000, v156
	v_lshlrev_b32_e32 v156, 16, v157
	v_and_b32_e32 v157, 0xffff0000, v157
	v_lshlrev_b32_e32 v160, 16, v158
	v_and_b32_e32 v161, 0xffff0000, v158
	v_lshlrev_b32_e32 v158, 16, v159
	v_and_b32_e32 v159, 0xffff0000, v159
	v_pk_add_f32 v[14:15], v[14:15], v[156:157]
	v_pk_add_f32 v[12:13], v[12:13], v[146:147]
	v_pk_add_f32 v[10:11], v[10:11], v[158:159]
	v_pk_add_f32 v[8:9], v[8:9], v[160:161]
	v_cvt_pk_bf16_f32 v156, v12, v13
	v_cvt_pk_bf16_f32 v157, v14, v15
	v_cvt_pk_bf16_f32 v158, v8, v9
	v_cvt_pk_bf16_f32 v159, v10, v11
	global_store_dwordx4 v[126:127], v[156:159], off
	global_load_dwordx4 v[156:159], v[126:127], off offset:256
	s_waitcnt vmcnt(0)
	v_lshlrev_b32_e32 v146, 16, v156
	v_and_b32_e32 v147, 0xffff0000, v156
	v_lshlrev_b32_e32 v156, 16, v157
	v_and_b32_e32 v157, 0xffff0000, v157
	v_lshlrev_b32_e32 v160, 16, v158
	v_and_b32_e32 v161, 0xffff0000, v158
	v_lshlrev_b32_e32 v158, 16, v159
	v_and_b32_e32 v159, 0xffff0000, v159
	v_pk_add_f32 v[6:7], v[6:7], v[156:157]
	v_pk_add_f32 v[4:5], v[4:5], v[146:147]
	v_pk_add_f32 v[2:3], v[2:3], v[158:159]
	v_pk_add_f32 v[0:1], v[0:1], v[160:161]
	v_cvt_pk_bf16_f32 v156, v4, v5
	v_cvt_pk_bf16_f32 v157, v6, v7
	v_cvt_pk_bf16_f32 v158, v0, v1
	v_cvt_pk_bf16_f32 v159, v2, v3
	global_store_dwordx4 v[126:127], v[156:159], off offset:256
	v_mov_b32_e32 v126, v155
	v_mov_b32_e32 v250, v155
	s_nop 1
	v_permlane16_swap_b32_e32 v250, v126
	s_waitcnt lgkmcnt(0)
	v_add_f32_e32 v127, v250, v126
	v_mov_b32_e32 v146, v127
	v_mov_b32_e32 v250, v127
	s_nop 1
	v_permlane32_swap_b32_e32 v250, v146
	v_add_u32_e32 v126, s18, v151
	s_and_saveexec_b64 s[22:23], s[40:41]
	s_cbranch_execz .LBB0_994
	s_waitcnt lgkmcnt(0)
	v_add_f32_e32 v127, v127, v146
	ds_write_b32 v126, v127
.LBB0_994:
	s_or_b64 exec, exec, s[22:23]
	v_mul_f32_e32 v105, v105, v105
	v_fmac_f32_e32 v105, v104, v104
	v_mul_f32_e32 v104, v107, v107
	v_mul_f32_e32 v109, v109, v109
	v_fmac_f32_e32 v104, v106, v106
	v_fmac_f32_e32 v109, v108, v108
	v_mul_f32_e32 v108, v111, v111
	v_add_f32_e32 v104, v105, v104
	v_mul_f32_e32 v105, v115, v115
	v_mul_f32_e32 v103, v103, v103
	v_mul_f32_e32 v101, v101, v101
	v_mul_f32_e32 v99, v99, v99
	v_fmac_f32_e32 v108, v110, v110
	v_fmac_f32_e32 v105, v114, v114
	v_fmac_f32_e32 v103, v102, v102
	v_fmac_f32_e32 v101, v100, v100
	v_fmac_f32_e32 v99, v98, v98
	v_add_f32_e32 v108, v109, v108
	v_add_f32_e32 v102, v105, v103
	v_add_f32_e32 v98, v101, v99
	v_add_f32_e32 v104, v108, v104
	v_add_f32_e32 v98, v102, v98
	v_add_f32_e32 v98, v104, v98
	v_mov_b32_e32 v99, v98
	v_mov_b32_e32 v250, v98
	s_nop 1
	v_permlane16_swap_b32_e32 v250, v99
	s_waitcnt lgkmcnt(0)
	v_add_f32_e32 v98, v250, v99
	v_mov_b32_e32 v99, v98
	v_mov_b32_e32 v250, v98
	s_nop 1
	v_permlane32_swap_b32_e32 v250, v99
	s_and_saveexec_b64 s[22:23], s[40:41]
	s_cbranch_execz .LBB0_996
	s_waitcnt lgkmcnt(0)
	v_add_f32_e32 v98, v98, v99
	ds_write_b32 v126, v98 offset:256
.LBB0_996:
	s_or_b64 exec, exec, s[22:23]
	v_mul_f32_e32 v89, v89, v89
	v_fmac_f32_e32 v89, v88, v88
	v_mul_f32_e32 v88, v91, v91
	v_mul_f32_e32 v93, v93, v93
	v_fmac_f32_e32 v88, v90, v90
	v_fmac_f32_e32 v93, v92, v92
	v_mul_f32_e32 v92, v95, v95
	v_add_f32_e32 v88, v89, v88
	v_mul_f32_e32 v89, v117, v117
	v_mul_f32_e32 v87, v87, v87
	v_mul_f32_e32 v85, v85, v85
	v_mul_f32_e32 v83, v83, v83
	v_fmac_f32_e32 v92, v94, v94
	v_fmac_f32_e32 v89, v116, v116
	v_fmac_f32_e32 v87, v86, v86
	v_fmac_f32_e32 v85, v84, v84
	v_fmac_f32_e32 v83, v82, v82
	v_add_f32_e32 v92, v93, v92
	v_add_f32_e32 v86, v89, v87
	v_add_f32_e32 v82, v85, v83
	v_add_f32_e32 v88, v92, v88
	v_add_f32_e32 v82, v86, v82
	v_add_f32_e32 v82, v88, v82
	v_mov_b32_e32 v83, v82
	v_mov_b32_e32 v250, v82
	s_nop 1
	v_permlane16_swap_b32_e32 v250, v83
	s_waitcnt lgkmcnt(0)
	v_add_f32_e32 v82, v250, v83
	v_mov_b32_e32 v83, v82
	v_mov_b32_e32 v250, v82
	s_nop 1
	v_permlane32_swap_b32_e32 v250, v83
	s_and_saveexec_b64 s[22:23], s[40:41]
	s_cbranch_execz .LBB0_998
	s_waitcnt lgkmcnt(0)
	v_add_f32_e32 v82, v82, v83
	ds_write_b32 v126, v82 offset:512
; template <bool ISMAX> DI void tile_row_reduce(float (&p)[2][4], LAS float* red, int wr, int wc, int fr, int fq) {
;     ...
;     for (int ai = 0; ai < 2; ++ai)
; #pragma unroll
;         for (int m = 0; m < 4; ++m) { float v = p[ai][m]; const float a = __shfl_xor(v, 16); v = ISMAX ? fmaxf(v, a) : v + a; const float b = __shfl_xor(v, 32); v = ISMAX ? fmaxf(v, b) : v + b;
;             if (fq == 0) red[(ai * 128 + wr * 64 + m * 16 + fr) * 4 + wc] = v; }
;     DI void operator()(Acc& acc, const Unit& u, int wr, int wc, int fr, int fq, LAS unsigned char* lds) const {
;     ...
;                         ss += ((v0.x * v0.x + v0.y * v0.y) + (v0.z * v0.z + v0.w * v0.w)) + ((v1.x * v1.x + v1.y * v1.y) + (v1.z * v1.z + v1.w * v1.w)); } }
;                 part[ai][m] = ss; }
.LBB0_998:
	s_or_b64 exec, exec, s[22:23]
	v_mul_f32_e32 v73, v73, v73
	v_fmac_f32_e32 v73, v72, v72
	v_mul_f32_e32 v72, v75, v75
	v_mul_f32_e32 v77, v77, v77
	v_fmac_f32_e32 v72, v74, v74
	v_fmac_f32_e32 v77, v76, v76
	v_mul_f32_e32 v76, v79, v79
	v_add_f32_e32 v72, v73, v72
	v_mul_f32_e32 v73, v119, v119
	v_mul_f32_e32 v71, v71, v71
	v_mul_f32_e32 v69, v69, v69
	v_mul_f32_e32 v67, v67, v67
	v_fmac_f32_e32 v76, v78, v78
	v_fmac_f32_e32 v73, v118, v118
	v_fmac_f32_e32 v71, v70, v70
	v_fmac_f32_e32 v69, v68, v68
	v_fmac_f32_e32 v67, v66, v66
	v_add_f32_e32 v76, v77, v76
	v_add_f32_e32 v70, v73, v71
	v_add_f32_e32 v66, v69, v67
	v_add_f32_e32 v72, v76, v72
	v_add_f32_e32 v66, v70, v66
	v_add_f32_e32 v66, v72, v66
	v_mov_b32_e32 v67, v66
	v_mov_b32_e32 v250, v66
	s_nop 1
	v_permlane16_swap_b32_e32 v250, v67
	s_waitcnt lgkmcnt(0)
	v_add_f32_e32 v66, v250, v67
	v_mov_b32_e32 v67, v66
	v_mov_b32_e32 v250, v66
	s_nop 1
	v_permlane32_swap_b32_e32 v250, v67
	s_and_saveexec_b64 s[22:23], s[40:41]
	s_cbranch_execz .LBB0_1000
	s_waitcnt lgkmcnt(0)
	v_add_f32_e32 v66, v66, v67
	ds_write_b32 v126, v66 offset:768
.LBB0_1000:
	s_or_b64 exec, exec, s[22:23]
	v_mul_f32_e32 v57, v57, v57
	v_fmac_f32_e32 v57, v56, v56
	v_mul_f32_e32 v56, v59, v59
	v_mul_f32_e32 v61, v61, v61
	v_fmac_f32_e32 v56, v58, v58
	v_fmac_f32_e32 v61, v60, v60
	v_mul_f32_e32 v60, v63, v63
	v_add_f32_e32 v56, v57, v56
	v_mul_f32_e32 v57, v121, v121
	v_mul_f32_e32 v55, v55, v55
	v_mul_f32_e32 v53, v53, v53
	v_mul_f32_e32 v51, v51, v51
	v_fmac_f32_e32 v60, v62, v62
	v_fmac_f32_e32 v57, v120, v120
	v_fmac_f32_e32 v55, v54, v54
	v_fmac_f32_e32 v53, v52, v52
	v_fmac_f32_e32 v51, v50, v50
	v_add_f32_e32 v60, v61, v60
	v_add_f32_e32 v54, v57, v55
	v_add_f32_e32 v50, v53, v51
	v_add_f32_e32 v56, v60, v56
	v_add_f32_e32 v50, v54, v50
	v_add_f32_e32 v50, v56, v50
	v_mov_b32_e32 v51, v50
	v_mov_b32_e32 v250, v50
	s_nop 1
	v_permlane16_swap_b32_e32 v250, v51
	s_waitcnt lgkmcnt(0)
	v_add_f32_e32 v50, v250, v51
	v_mov_b32_e32 v51, v50
	v_mov_b32_e32 v250, v50
	s_nop 1
	v_permlane32_swap_b32_e32 v250, v51
	s_and_saveexec_b64 s[22:23], s[40:41]
	s_cbranch_execz .LBB0_1002
	s_waitcnt lgkmcnt(0)
	v_add_f32_e32 v50, v50, v51
	ds_write_b32 v126, v50 offset:2048
.LBB0_1002:
	s_or_b64 exec, exec, s[22:23]
	v_mul_f32_e32 v41, v41, v41
	v_fmac_f32_e32 v41, v40, v40
	v_mul_f32_e32 v40, v43, v43
	v_mul_f32_e32 v45, v45, v45
	v_fmac_f32_e32 v40, v42, v42
	v_fmac_f32_e32 v45, v44, v44
	v_mul_f32_e32 v44, v47, v47
	v_add_f32_e32 v40, v41, v40
	v_mul_f32_e32 v41, v123, v123
	v_mul_f32_e32 v39, v39, v39
	v_mul_f32_e32 v37, v37, v37
	v_mul_f32_e32 v35, v35, v35
	v_fmac_f32_e32 v44, v46, v46
	v_fmac_f32_e32 v41, v122, v122
	v_fmac_f32_e32 v39, v38, v38
	v_fmac_f32_e32 v37, v36, v36
	v_fmac_f32_e32 v35, v34, v34
	v_add_f32_e32 v44, v45, v44
	v_add_f32_e32 v38, v41, v39
	v_add_f32_e32 v34, v37, v35
	v_add_f32_e32 v40, v44, v40
	v_add_f32_e32 v34, v38, v34
	v_add_f32_e32 v34, v40, v34
	v_mov_b32_e32 v35, v34
	v_mov_b32_e32 v250, v34
	s_nop 1
	v_permlane16_swap_b32_e32 v250, v35
	s_waitcnt lgkmcnt(0)
	v_add_f32_e32 v34, v250, v35
	v_mov_b32_e32 v35, v34
	v_mov_b32_e32 v250, v34
	s_nop 1
	v_permlane32_swap_b32_e32 v250, v35
	s_and_saveexec_b64 s[22:23], s[40:41]
	s_cbranch_execz .LBB0_1004
	s_waitcnt lgkmcnt(0)
	v_add_f32_e32 v34, v34, v35
	ds_write_b32 v126, v34 offset:2304
.LBB0_1004:
	s_or_b64 exec, exec, s[22:23]
	v_mul_f32_e32 v25, v25, v25
	v_fmac_f32_e32 v25, v24, v24
	v_mul_f32_e32 v24, v27, v27
	v_mul_f32_e32 v29, v29, v29
	v_fmac_f32_e32 v24, v26, v26
	v_fmac_f32_e32 v29, v28, v28
	v_mul_f32_e32 v28, v31, v31
	v_add_f32_e32 v24, v25, v24
	v_mul_f32_e32 v25, v125, v125
	v_mul_f32_e32 v23, v23, v23
	v_mul_f32_e32 v21, v21, v21
	v_mul_f32_e32 v19, v19, v19
	v_fmac_f32_e32 v28, v30, v30
	v_fmac_f32_e32 v25, v124, v124
	v_fmac_f32_e32 v23, v22, v22
	v_fmac_f32_e32 v21, v20, v20
	v_fmac_f32_e32 v19, v18, v18
	v_add_f32_e32 v28, v29, v28
	v_add_f32_e32 v22, v25, v23
	v_add_f32_e32 v18, v21, v19
	v_add_f32_e32 v24, v28, v24
	v_add_f32_e32 v18, v22, v18
	v_add_f32_e32 v18, v24, v18
	v_mov_b32_e32 v19, v18
	v_mov_b32_e32 v250, v18
	s_nop 1
	v_permlane16_swap_b32_e32 v250, v19
	s_waitcnt lgkmcnt(0)
	v_add_f32_e32 v18, v250, v19
	v_mov_b32_e32 v19, v18
	v_mov_b32_e32 v250, v18
	s_nop 1
	v_permlane32_swap_b32_e32 v250, v19
	s_and_saveexec_b64 s[22:23], s[40:41]
	s_cbranch_execz .LBB0_1006
	s_waitcnt lgkmcnt(0)
	v_add_f32_e32 v18, v18, v19
	ds_write_b32 v126, v18 offset:2560
.LBB0_1006:
	s_or_b64 exec, exec, s[22:23]
	v_mul_f32_e32 v13, v13, v13
	v_mul_f32_e32 v9, v9, v9
	v_mul_f32_e32 v5, v5, v5
	v_mul_f32_e32 v1, v1, v1
	v_fmac_f32_e32 v13, v12, v12
	v_mul_f32_e32 v12, v15, v15
	v_fmac_f32_e32 v9, v8, v8
	v_mul_f32_e32 v8, v11, v11
	v_fmac_f32_e32 v5, v4, v4
	v_mul_f32_e32 v4, v7, v7
	v_fmac_f32_e32 v1, v0, v0
	v_mul_f32_e32 v0, v3, v3
	v_fmac_f32_e32 v12, v14, v14
	v_fmac_f32_e32 v8, v10, v10
	v_fmac_f32_e32 v4, v6, v6
	v_fmac_f32_e32 v0, v2, v2
	v_add_f32_e32 v12, v13, v12
	v_add_f32_e32 v8, v9, v8
	v_add_f32_e32 v4, v5, v4
	v_add_f32_e32 v0, v1, v0
	v_add_f32_e32 v8, v12, v8
	v_add_f32_e32 v0, v4, v0
	v_add_f32_e32 v0, v8, v0
	v_mov_b32_e32 v1, v0
	v_mov_b32_e32 v250, v0
	s_nop 1
	v_permlane16_swap_b32_e32 v250, v1
	s_waitcnt lgkmcnt(0)
	v_add_f32_e32 v0, v250, v1
	v_mov_b32_e32 v1, v0
	v_mov_b32_e32 v250, v0
	s_nop 1
	v_permlane32_swap_b32_e32 v250, v1
	s_and_saveexec_b64 s[22:23], s[40:41]
	s_cbranch_execz .LBB0_1008
	s_waitcnt lgkmcnt(0)
	v_add_f32_e32 v0, v0, v1
	ds_write_b32 v126, v0 offset:2816
